# speedup vs baseline: 1.0324x; 1.0010x over previous
; #define WAIT_V(n) asm volatile("s_waitcnt vmcnt(" #n ")" ::: "memory")
; #define BAR __builtin_amdgcn_s_barrier()
; template <int K, bool SWAP>
; __device__ __forceinline__ void gemm_kloop(const bf16* __restrict__ A, const bf16* __restrict__ Bt,
;                                            f32x4 (&acc)[2][2][4][2], bool pref = false) {
;     ...
;   int tidx = threadIdx.x;
;   asm volatile("" : "+v"(tidx));
;   const int wid = tidx >> 6, lane = tidx & 63, wr = wid >> 2, wc = wid & 3, fr = lane & 15, fq = lane >> 4;
;   bf16x8 At[4][2], B0[2][2], B1[2][2];
;   constexpr int nt = K / BK;
;   if (!pref) {
;     STAGE(SB(0, 0), Bt, 0, 0); STAGE(SA(0, 0), A, 0, 0);
;     STAGE(SB(0, 1), Bt, HALF, 0); STAGE(SA(0, 1), A, HALF, 0);
;   }
;   if (wr == 1) BAR;
;   WAIT_V(4); BAR;
;   STAGE(SB(1, 0), Bt, 0, 1); STAGE(SA(1, 0), A, 0, 1); STAGE(SB(1, 1), Bt, HALF, 1);
;   WAIT_V(6); BAR;
.LBB0_270:
	s_or_b64 exec, exec, s[14:15]
	v_add_u32_e32 v1, v145, v1
	v_and_b32_e32 v1, 0xfffffc00, v1
	v_sub_u32_e32 v1, v145, v1
	v_lshrrev_b32_e32 v4, 4, v1
	v_bitop3_b32 v1, v4, v1, 32 bitop3:0x6c
	v_ashrrev_i32_e32 v5, 31, v1
	v_lshrrev_b32_e32 v5, 26, v5
	v_add_u32_e32 v2, v144, v2
	v_add_u32_e32 v5, v1, v5
	v_ashrrev_i32_e32 v2, 6, v2
	v_ashrrev_i32_e32 v6, 6, v5
	v_and_b32_e32 v5, 0xc0, v5
	v_lshlrev_b32_e32 v4, 3, v2
	v_lshlrev_b32_e32 v2, 5, v2
	v_sub_u32_e32 v1, v1, v5
	v_and_b32_e32 v4, -16, v4
	v_and_b32_e32 v2, 32, v2
	v_ashrrev_i16_sdwa v1, v193, sext(v1) dst_sel:DWORD dst_unused:UNUSED_PAD src0_sel:DWORD src1_sel:BYTE_0
	v_add_u32_e32 v4, v6, v4
	v_add_u32_sdwa v128, v2, sext(v1) dst_sel:DWORD dst_unused:UNUSED_PAD src0_sel:DWORD src1_sel:WORD_0
	v_ashrrev_i32_e32 v1, 31, v0
	v_ashrrev_i32_e32 v5, 31, v4
	v_lshrrev_b32_e32 v1, 22, v1
	v_lshlrev_b64 v[130:131], 11, v[4:5]
	v_ashrrev_i32_e32 v129, 31, v128
	v_readlane_b32 s9, v254, 33
	v_add_u32_e32 v1, v0, v1
	v_lshl_add_u64 v[4:5], s[12:13], 0, v[130:131]
	v_lshlrev_b64 v[6:7], 1, v[128:129]
	v_add_u32_e32 v154, s9, v145
	v_ashrrev_i32_e32 v1, 10, v1
	v_lshl_add_u64 v[4:5], v[4:5], 0, v[6:7]
	s_mov_b64 s[14:15], 0x80
	v_readfirstlane_b32 s7, v154
	v_mul_i32_i24_e32 v2, 0x400, v1
	v_lshl_add_u64 v[4:5], v[4:5], 0, s[14:15]
	s_mov_b32 m0, s7
	v_sub_u32_e32 v2, v0, v2
	s_waitcnt vmcnt(4)
	s_barrier
	global_load_lds_dwordx4 v[4:5], off
	v_lshrrev_b32_e32 v4, 4, v2
	v_bitop3_b32 v2, v4, v2, 32 bitop3:0x6c
	v_ashrrev_i32_e32 v5, 31, v2
	v_lshrrev_b32_e32 v5, 26, v5
	v_add_u32_e32 v5, v2, v5
	v_lshlrev_b32_e32 v4, 3, v1
	v_ashrrev_i32_e32 v8, 6, v5
	v_and_b32_e32 v5, 0xc0, v5
	v_and_b32_e32 v4, -16, v4
	v_lshlrev_b32_e32 v1, 5, v1
	v_sub_u32_e32 v2, v2, v5
	v_add_u32_e32 v4, v8, v4
	v_and_b32_e32 v1, 32, v1
	v_ashrrev_i16_sdwa v2, v193, sext(v2) dst_sel:DWORD dst_unused:UNUSED_PAD src0_sel:DWORD src1_sel:BYTE_0
	v_add_u32_sdwa v132, v1, sext(v2) dst_sel:DWORD dst_unused:UNUSED_PAD src0_sel:DWORD src1_sel:WORD_0
	v_ashrrev_i32_e32 v5, 31, v4
	v_lshlrev_b64 v[134:135], 11, v[4:5]
	v_ashrrev_i32_e32 v133, 31, v132
	v_lshl_add_u64 v[4:5], s[12:13], 0, v[134:135]
	v_lshlrev_b64 v[8:9], 1, v[132:133]
	v_add_u32_e32 v1, s9, v0
	v_lshl_add_u64 v[4:5], v[4:5], 0, v[8:9]
	v_readfirstlane_b32 s7, v1
	v_lshl_add_u64 v[4:5], v[4:5], 0, s[14:15]
	s_mov_b32 m0, s7
	v_add_u32_e32 v155, 0x8000, v146
	global_load_lds_dwordx4 v[4:5], off
	v_lshl_add_u64 v[4:5], s[0:1], 0, v[130:131]
	v_lshl_add_u64 v[4:5], v[4:5], 0, v[6:7]
	v_readfirstlane_b32 s7, v155
	v_lshl_add_u64 v[4:5], v[4:5], 0, s[14:15]
	s_mov_b32 m0, s7
	v_add_u32_e32 v156, 0xa000, v146
	global_load_lds_dwordx4 v[4:5], off
	v_lshl_add_u64 v[4:5], s[0:1], 0, v[134:135]
	v_lshl_add_u64 v[4:5], v[4:5], 0, v[8:9]
	v_lshl_add_u64 v[4:5], v[4:5], 0, s[14:15]
	v_readfirstlane_b32 s7, v156
	s_add_u32 s12, s12, 0x40080
	v_readlane_b32 s14, v254, 34
	s_mov_b32 m0, s7
	s_addc_u32 s13, s13, 0
	v_add_u32_e32 v157, s14, v145
	global_load_lds_dwordx4 v[4:5], off
	v_lshl_add_u64 v[4:5], s[12:13], 0, v[130:131]
	v_readfirstlane_b32 s7, v157
	v_lshl_add_u64 v[4:5], v[4:5], 0, v[6:7]
	s_mov_b32 m0, s7
	v_add_u32_e32 v0, s14, v0
	global_load_lds_dwordx4 v[4:5], off
	v_lshl_add_u64 v[4:5], s[12:13], 0, v[134:135]
	v_readfirstlane_b32 s7, v0
	v_lshl_add_u64 v[4:5], v[4:5], 0, v[8:9]
	s_mov_b32 m0, s7
	v_and_b32_e32 v10, 15, v144
	global_load_lds_dwordx4 v[4:5], off
	v_lshlrev_b32_e32 v1, 2, v144
	v_and_b32_e32 v11, 48, v144
	v_lshlrev_b32_e32 v0, 6, v10
	v_and_b32_e32 v1, 32, v1
	v_bitop3_b32 v0, v0, v1, v11 bitop3:0x36
	s_add_i32 s7, 0, 0x10000
	v_add_u32_e32 v5, s9, v0
	v_lshlrev_b32_e32 v12, 6, v144
	s_movk_i32 s9, 0x3c0
	s_add_u32 s10, s70, s10
	v_add_u32_e32 v2, s7, v0
	v_add_u32_e32 v4, s33, v0
	v_add_u32_e32 v10, s14, v0
	v_add_u32_e32 v14, 0, v0
	v_and_or_b32 v0, v12, s9, v11
	s_addc_u32 s11, 0, s11
	v_xad_u32 v11, v0, v1, 0
	v_lshl_add_u64 v[0:1], s[10:11], 0, v[130:131]
	v_lshl_add_u64 v[136:137], v[0:1], 0, v[6:7]
	v_lshl_add_u64 v[0:1], s[10:11], 0, v[134:135]
	s_waitcnt vmcnt(6)
	v_lshl_add_u64 v[138:139], v[0:1], 0, v[8:9]
	v_lshl_add_u64 v[0:1], s[4:5], 0, v[130:131]
	v_lshlrev_b32_e32 v3, 13, v3
	v_lshl_add_u64 v[140:141], v[0:1], 0, v[6:7]
	v_lshl_add_u64 v[0:1], s[4:5], 0, v[134:135]
	v_and_b32_e32 v13, 0x3000, v12
	v_or_b32_e32 v12, 0x800, v3
	v_or_b32_e32 v15, 0x1000, v3
	v_or_b32_e32 v16, 0x1800, v3
	v_lshl_add_u64 v[142:143], v[0:1], 0, v[8:9]
	v_mov_b32_e32 v0, 0
	s_barrier
; __device__ __forceinline__ void zero_acc(f32x4 (&acc)[2][2][4][2]) {
;   _Pragma("unroll") for (int a = 0; a < 2; ++a) _Pragma("unroll") for (int b = 0; b < 2; ++b) _Pragma("unroll") for (int m = 0; m < 4; ++m) _Pragma("unroll") for (int n = 0; n < 2; ++n)
;     acc[a][b][m][n] = f32x4{0.f, 0.f, 0.f, 0.f};
; }
	s_mov_b32 s4, -2
	v_add_u32_e32 v159, v2, v13
	v_add_u32_e32 v151, v14, v3
	v_add_u32_e32 v150, v11, v12
	v_add_u32_e32 v149, v11, v15
	v_add_u32_e32 v148, v11, v16
	v_add_u32_e32 v158, v4, v13
	v_add_u32_e32 v153, v5, v13
	v_add_u32_e32 v152, v10, v13
	v_mov_b32_e32 v1, v0
	v_mov_b32_e32 v2, v0
	v_mov_b32_e32 v3, v0
	v_mov_b32_e32 v4, v0
	v_mov_b32_e32 v5, v0
	v_mov_b32_e32 v6, v0
	v_mov_b32_e32 v7, v0
	v_mov_b32_e32 v8, v0
	v_mov_b32_e32 v9, v0
	v_mov_b32_e32 v10, v0
	v_mov_b32_e32 v11, v0
	v_mov_b32_e32 v12, v0
	v_mov_b32_e32 v13, v0
	v_mov_b32_e32 v14, v0
	v_mov_b32_e32 v15, v0
	v_mov_b32_e32 v16, v0
	v_mov_b32_e32 v17, v0
	v_mov_b32_e32 v18, v0
	v_mov_b32_e32 v19, v0
	v_mov_b32_e32 v20, v0
	v_mov_b32_e32 v21, v0
	v_mov_b32_e32 v22, v0
	v_mov_b32_e32 v23, v0
	v_mov_b32_e32 v24, v0
	v_mov_b32_e32 v25, v0
	v_mov_b32_e32 v26, v0
	v_mov_b32_e32 v27, v0
	v_mov_b32_e32 v28, v0
	v_mov_b32_e32 v29, v0
	v_mov_b32_e32 v30, v0
	v_mov_b32_e32 v31, v0
	v_mov_b32_e32 v32, v0
	v_mov_b32_e32 v33, v0
	v_mov_b32_e32 v34, v0
	v_mov_b32_e32 v35, v0
	v_mov_b32_e32 v36, v0
	v_mov_b32_e32 v37, v0
	v_mov_b32_e32 v38, v0
	v_mov_b32_e32 v39, v0
	v_mov_b32_e32 v40, v0
	v_mov_b32_e32 v41, v0
	v_mov_b32_e32 v42, v0
	v_mov_b32_e32 v43, v0
	v_mov_b32_e32 v44, v0
	v_mov_b32_e32 v45, v0
	v_mov_b32_e32 v46, v0
	v_mov_b32_e32 v47, v0
	v_mov_b32_e32 v48, v0
	v_mov_b32_e32 v49, v0
	v_mov_b32_e32 v50, v0
	v_mov_b32_e32 v51, v0
	v_mov_b32_e32 v52, v0
	v_mov_b32_e32 v53, v0
	v_mov_b32_e32 v54, v0
	v_mov_b32_e32 v55, v0
	v_mov_b32_e32 v56, v0
	v_mov_b32_e32 v57, v0
	v_mov_b32_e32 v58, v0
	v_mov_b32_e32 v59, v0
	v_mov_b32_e32 v60, v0
	v_mov_b32_e32 v61, v0
	v_mov_b32_e32 v62, v0
	v_mov_b32_e32 v63, v0
	v_mov_b32_e32 v64, v0
	v_mov_b32_e32 v65, v0
	v_mov_b32_e32 v66, v0
	v_mov_b32_e32 v67, v0
	v_mov_b32_e32 v68, v0
	v_mov_b32_e32 v69, v0
	v_mov_b32_e32 v70, v0
	v_mov_b32_e32 v71, v0
	v_mov_b32_e32 v72, v0
	v_mov_b32_e32 v73, v0
	v_mov_b32_e32 v74, v0
	v_mov_b32_e32 v75, v0
	v_mov_b32_e32 v76, v0
	v_mov_b32_e32 v77, v0
	v_mov_b32_e32 v78, v0
	v_mov_b32_e32 v79, v0
	v_mov_b32_e32 v80, v0
	v_mov_b32_e32 v81, v0
	v_mov_b32_e32 v82, v0
	v_mov_b32_e32 v83, v0
	v_mov_b32_e32 v84, v0
	v_mov_b32_e32 v85, v0
	v_mov_b32_e32 v86, v0
	v_mov_b32_e32 v87, v0
	v_mov_b32_e32 v88, v0
	v_mov_b32_e32 v89, v0
	v_mov_b32_e32 v90, v0
	v_mov_b32_e32 v91, v0
	v_mov_b32_e32 v92, v0
	v_mov_b32_e32 v93, v0
	v_mov_b32_e32 v94, v0
	v_mov_b32_e32 v95, v0
	v_mov_b32_e32 v96, v0
	v_mov_b32_e32 v97, v0
	v_mov_b32_e32 v98, v0
	v_mov_b32_e32 v99, v0
	v_mov_b32_e32 v100, v0
	v_mov_b32_e32 v101, v0
	v_mov_b32_e32 v102, v0
	v_mov_b32_e32 v103, v0
	v_mov_b32_e32 v104, v0
	v_mov_b32_e32 v105, v0
	v_mov_b32_e32 v106, v0
	v_mov_b32_e32 v107, v0
	v_mov_b32_e32 v108, v0
	v_mov_b32_e32 v109, v0
	v_mov_b32_e32 v110, v0
	v_mov_b32_e32 v111, v0
	v_mov_b32_e32 v112, v0
	v_mov_b32_e32 v113, v0
	v_mov_b32_e32 v114, v0
	v_mov_b32_e32 v115, v0
	v_mov_b32_e32 v116, v0
	v_mov_b32_e32 v117, v0
	v_mov_b32_e32 v118, v0
	v_mov_b32_e32 v119, v0
	v_mov_b32_e32 v120, v0
	v_mov_b32_e32 v121, v0
	v_mov_b32_e32 v122, v0
	v_mov_b32_e32 v123, v0
	v_mov_b32_e32 v124, v0
	v_mov_b32_e32 v125, v0
	v_mov_b32_e32 v126, v0
	v_mov_b32_e32 v127, v0
	.p2align	6

; #define WAIT_V(n) asm volatile("s_waitcnt vmcnt(" #n ")" ::: "memory")
; #define BAR __builtin_amdgcn_s_barrier()
; template <int K, bool SWAP>
; __device__ __forceinline__ void gemm_kloop(const bf16* __restrict__ A, const bf16* __restrict__ Bt,
;                                            f32x4 (&acc)[2][2][4][2], bool pref = false) {
;     ...
;   if (wr == 1) BAR;
;   WAIT_V(4); BAR;
.LBB0_448:
	s_or_b64 exec, exec, s[12:13]
	v_add_u32_e32 v1, v145, v1
	v_and_b32_e32 v1, 0xfffffc00, v1
	v_sub_u32_e32 v1, v145, v1
	v_lshrrev_b32_e32 v4, 4, v1
	v_bitop3_b32 v1, v4, v1, 32 bitop3:0x6c
	v_ashrrev_i32_e32 v5, 31, v1
	v_lshrrev_b32_e32 v5, 26, v5
	v_add_u32_e32 v2, v144, v2
	v_add_u32_e32 v5, v1, v5
	v_ashrrev_i32_e32 v2, 6, v2
	v_ashrrev_i32_e32 v6, 6, v5
	v_and_b32_e32 v5, 0xc0, v5
	v_lshlrev_b32_e32 v4, 3, v2
	v_lshlrev_b32_e32 v2, 5, v2
	v_sub_u32_e32 v1, v1, v5
	v_and_b32_e32 v4, -16, v4
	v_and_b32_e32 v2, 32, v2
	v_ashrrev_i16_sdwa v1, v193, sext(v1) dst_sel:DWORD dst_unused:UNUSED_PAD src0_sel:DWORD src1_sel:BYTE_0
	v_add_u32_e32 v4, v6, v4
	v_add_u32_sdwa v128, v2, sext(v1) dst_sel:DWORD dst_unused:UNUSED_PAD src0_sel:DWORD src1_sel:WORD_0
	v_ashrrev_i32_e32 v1, 31, v0
	v_ashrrev_i32_e32 v5, 31, v4
	v_lshrrev_b32_e32 v1, 22, v1
	v_lshlrev_b64 v[130:131], 11, v[4:5]
	v_ashrrev_i32_e32 v129, 31, v128
	v_readlane_b32 s15, v254, 33
	v_add_u32_e32 v1, v0, v1
	v_lshl_add_u64 v[4:5], s[10:11], 0, v[130:131]
	v_lshlrev_b64 v[6:7], 1, v[128:129]
	v_add_u32_e32 v154, s15, v145
	v_ashrrev_i32_e32 v1, 10, v1
	v_lshl_add_u64 v[4:5], v[4:5], 0, v[6:7]
	s_mov_b64 s[12:13], 0x80
	v_readfirstlane_b32 s1, v154
	v_mul_i32_i24_e32 v2, 0x400, v1
	v_lshl_add_u64 v[4:5], v[4:5], 0, s[12:13]
	s_mov_b32 m0, s1
	v_sub_u32_e32 v2, v0, v2
	s_waitcnt vmcnt(4)
	s_barrier
; #define WAIT_V(n) asm volatile("s_waitcnt vmcnt(" #n ")" ::: "memory")
; #define BAR __builtin_amdgcn_s_barrier()
; template <int K, bool SWAP>
; __device__ __forceinline__ void gemm_kloop(const bf16* __restrict__ A, const bf16* __restrict__ Bt,
;                                            f32x4 (&acc)[2][2][4][2], bool pref = false) {
;     ...
;   int tidx = threadIdx.x;
;   asm volatile("" : "+v"(tidx));
;   const int wid = tidx >> 6, lane = tidx & 63, wr = wid >> 2, wc = wid & 3, fr = lane & 15, fq = lane >> 4;
;   bf16x8 At[4][2], B0[2][2], B1[2][2];
;   constexpr int nt = K / BK;
;   if (!pref) {
;     STAGE(SB(0, 0), Bt, 0, 0); STAGE(SA(0, 0), A, 0, 0);
;     STAGE(SB(0, 1), Bt, HALF, 0); STAGE(SA(0, 1), A, HALF, 0);
;   }
;   if (wr == 1) BAR;
;   WAIT_V(4); BAR;
;   STAGE(SB(1, 0), Bt, 0, 1); STAGE(SA(1, 0), A, 0, 1); STAGE(SB(1, 1), Bt, HALF, 1);
;   WAIT_V(6); BAR;
; __device__ __forceinline__ void zero_acc(f32x4 (&acc)[2][2][4][2]) {
;   _Pragma("unroll") for (int a = 0; a < 2; ++a) _Pragma("unroll") for (int b = 0; b < 2; ++b) _Pragma("unroll") for (int m = 0; m < 4; ++m) _Pragma("unroll") for (int n = 0; n < 2; ++n)
;     acc[a][b][m][n] = f32x4{0.f, 0.f, 0.f, 0.f};
; }
	global_load_lds_dwordx4 v[4:5], off
	v_lshrrev_b32_e32 v4, 4, v2
	v_bitop3_b32 v2, v4, v2, 32 bitop3:0x6c
	v_ashrrev_i32_e32 v5, 31, v2
	v_lshrrev_b32_e32 v5, 26, v5
	v_add_u32_e32 v5, v2, v5
	v_lshlrev_b32_e32 v4, 3, v1
	v_ashrrev_i32_e32 v8, 6, v5
	v_and_b32_e32 v5, 0xc0, v5
	v_and_b32_e32 v4, -16, v4
	v_lshlrev_b32_e32 v1, 5, v1
	v_sub_u32_e32 v2, v2, v5
	v_add_u32_e32 v4, v8, v4
	v_and_b32_e32 v1, 32, v1
	v_ashrrev_i16_sdwa v2, v193, sext(v2) dst_sel:DWORD dst_unused:UNUSED_PAD src0_sel:DWORD src1_sel:BYTE_0
	v_add_u32_sdwa v132, v1, sext(v2) dst_sel:DWORD dst_unused:UNUSED_PAD src0_sel:DWORD src1_sel:WORD_0
	v_ashrrev_i32_e32 v5, 31, v4
	v_lshlrev_b64 v[134:135], 11, v[4:5]
	v_ashrrev_i32_e32 v133, 31, v132
	v_lshl_add_u64 v[4:5], s[10:11], 0, v[134:135]
	v_lshlrev_b64 v[8:9], 1, v[132:133]
	v_add_u32_e32 v1, s15, v0
	v_lshl_add_u64 v[4:5], v[4:5], 0, v[8:9]
	v_readfirstlane_b32 s1, v1
	v_lshl_add_u64 v[4:5], v[4:5], 0, s[12:13]
	s_mov_b32 m0, s1
	v_add_u32_e32 v155, 0x8000, v146
	global_load_lds_dwordx4 v[4:5], off
	v_lshl_add_u64 v[4:5], s[4:5], 0, v[130:131]
	v_lshl_add_u64 v[4:5], v[4:5], 0, v[6:7]
	v_readfirstlane_b32 s1, v155
	v_lshl_add_u64 v[4:5], v[4:5], 0, s[12:13]
	s_mov_b32 m0, s1
	v_add_u32_e32 v156, 0xa000, v146
	global_load_lds_dwordx4 v[4:5], off
	v_lshl_add_u64 v[4:5], s[4:5], 0, v[134:135]
	v_lshl_add_u64 v[4:5], v[4:5], 0, v[8:9]
	v_lshl_add_u64 v[4:5], v[4:5], 0, s[12:13]
	v_readfirstlane_b32 s1, v156
	s_add_u32 s10, s10, 0x40080
	v_readlane_b32 s12, v254, 34
	s_mov_b32 m0, s1
	s_addc_u32 s11, s11, 0
	v_add_u32_e32 v157, s12, v145
	global_load_lds_dwordx4 v[4:5], off
	v_lshl_add_u64 v[4:5], s[10:11], 0, v[130:131]
	v_readfirstlane_b32 s1, v157
	v_lshl_add_u64 v[4:5], v[4:5], 0, v[6:7]
	s_mov_b32 m0, s1
	v_add_u32_e32 v0, s12, v0
	global_load_lds_dwordx4 v[4:5], off
	v_lshl_add_u64 v[4:5], s[10:11], 0, v[134:135]
	v_readfirstlane_b32 s1, v0
	v_lshl_add_u64 v[4:5], v[4:5], 0, v[8:9]
	s_mov_b32 m0, s1
	v_and_b32_e32 v10, 15, v144
	global_load_lds_dwordx4 v[4:5], off
	v_lshlrev_b32_e32 v1, 2, v144
	v_and_b32_e32 v11, 48, v144
	v_lshlrev_b32_e32 v0, 6, v10
	v_and_b32_e32 v1, 32, v1
	s_add_i32 s1, 0, 0x10000
	v_bitop3_b32 v0, v0, v1, v11 bitop3:0x36
	v_lshlrev_b32_e32 v12, 6, v144
	s_movk_i32 s10, 0x3c0
	s_add_u32 s8, s70, s8
	v_add_u32_e32 v2, s1, v0
	v_add_u32_e32 v4, s33, v0
	v_add_u32_e32 v5, s15, v0
	v_add_u32_e32 v10, s12, v0
	v_add_u32_e32 v14, 0, v0
	v_and_or_b32 v0, v12, s10, v11
	s_addc_u32 s9, 0, s9
	v_xad_u32 v11, v0, v1, 0
	v_lshl_add_u64 v[0:1], s[8:9], 0, v[130:131]
	v_lshl_add_u64 v[136:137], v[0:1], 0, v[6:7]
	v_lshl_add_u64 v[0:1], s[8:9], 0, v[134:135]
	v_lshl_add_u64 v[138:139], v[0:1], 0, v[8:9]
	v_lshl_add_u64 v[0:1], s[6:7], 0, v[130:131]
	s_waitcnt vmcnt(6)
	v_lshlrev_b32_e32 v3, 13, v3
	v_lshl_add_u64 v[140:141], v[0:1], 0, v[6:7]
	v_lshl_add_u64 v[0:1], s[6:7], 0, v[134:135]
	v_and_b32_e32 v13, 0x3000, v12
	v_or_b32_e32 v12, 0x800, v3
	v_or_b32_e32 v15, 0x1000, v3
	v_or_b32_e32 v16, 0x1800, v3
	v_lshl_add_u64 v[142:143], v[0:1], 0, v[8:9]
	v_mov_b32_e32 v0, 0
	s_mov_b32 s6, -2
	v_add_u32_e32 v159, v2, v13
	v_add_u32_e32 v151, v14, v3
	v_add_u32_e32 v150, v11, v12
	v_add_u32_e32 v149, v11, v15
	v_add_u32_e32 v148, v11, v16
	v_add_u32_e32 v158, v4, v13
	v_add_u32_e32 v153, v5, v13
	v_add_u32_e32 v152, v10, v13
	v_mov_b32_e32 v1, v0
	v_mov_b32_e32 v2, v0
	v_mov_b32_e32 v3, v0
	v_mov_b32_e32 v4, v0
	v_mov_b32_e32 v5, v0
	v_mov_b32_e32 v6, v0
	v_mov_b32_e32 v7, v0
	v_mov_b32_e32 v8, v0
	v_mov_b32_e32 v9, v0
	v_mov_b32_e32 v10, v0
	v_mov_b32_e32 v11, v0
	v_mov_b32_e32 v12, v0
	v_mov_b32_e32 v13, v0
	v_mov_b32_e32 v14, v0
	v_mov_b32_e32 v15, v0
	v_mov_b32_e32 v16, v0
	v_mov_b32_e32 v17, v0
	v_mov_b32_e32 v18, v0
	v_mov_b32_e32 v19, v0
	v_mov_b32_e32 v20, v0
	v_mov_b32_e32 v21, v0
	v_mov_b32_e32 v22, v0
	v_mov_b32_e32 v23, v0
	v_mov_b32_e32 v24, v0
	v_mov_b32_e32 v25, v0
	v_mov_b32_e32 v26, v0
	v_mov_b32_e32 v27, v0
	v_mov_b32_e32 v28, v0
	v_mov_b32_e32 v29, v0
	v_mov_b32_e32 v30, v0
	v_mov_b32_e32 v31, v0
	v_mov_b32_e32 v32, v0
	v_mov_b32_e32 v33, v0
	v_mov_b32_e32 v34, v0
	v_mov_b32_e32 v35, v0
	v_mov_b32_e32 v36, v0
	v_mov_b32_e32 v37, v0
	v_mov_b32_e32 v38, v0
	v_mov_b32_e32 v39, v0
	v_mov_b32_e32 v40, v0
	v_mov_b32_e32 v41, v0
	v_mov_b32_e32 v42, v0
	v_mov_b32_e32 v43, v0
	v_mov_b32_e32 v44, v0
	v_mov_b32_e32 v45, v0
	v_mov_b32_e32 v46, v0
	v_mov_b32_e32 v47, v0
	v_mov_b32_e32 v48, v0
	v_mov_b32_e32 v49, v0
	v_mov_b32_e32 v50, v0
	v_mov_b32_e32 v51, v0
	v_mov_b32_e32 v52, v0
	v_mov_b32_e32 v53, v0
	v_mov_b32_e32 v54, v0
	v_mov_b32_e32 v55, v0
	v_mov_b32_e32 v56, v0
	v_mov_b32_e32 v57, v0
	v_mov_b32_e32 v58, v0
	v_mov_b32_e32 v59, v0
	v_mov_b32_e32 v60, v0
	v_mov_b32_e32 v61, v0
	v_mov_b32_e32 v62, v0
	v_mov_b32_e32 v63, v0
	v_mov_b32_e32 v64, v0
	v_mov_b32_e32 v65, v0
	v_mov_b32_e32 v66, v0
	v_mov_b32_e32 v67, v0
	v_mov_b32_e32 v68, v0
	v_mov_b32_e32 v69, v0
	v_mov_b32_e32 v70, v0
	v_mov_b32_e32 v71, v0
	v_mov_b32_e32 v72, v0
	v_mov_b32_e32 v73, v0
	v_mov_b32_e32 v74, v0
	v_mov_b32_e32 v75, v0
	v_mov_b32_e32 v76, v0
	v_mov_b32_e32 v77, v0
	v_mov_b32_e32 v78, v0
	v_mov_b32_e32 v79, v0
	v_mov_b32_e32 v80, v0
	v_mov_b32_e32 v81, v0
	v_mov_b32_e32 v82, v0
	v_mov_b32_e32 v83, v0
	v_mov_b32_e32 v84, v0
	v_mov_b32_e32 v85, v0
	v_mov_b32_e32 v86, v0
	v_mov_b32_e32 v87, v0
	v_mov_b32_e32 v88, v0
	v_mov_b32_e32 v89, v0
	v_mov_b32_e32 v90, v0
	v_mov_b32_e32 v91, v0
	v_mov_b32_e32 v92, v0
	v_mov_b32_e32 v93, v0
	v_mov_b32_e32 v94, v0
	v_mov_b32_e32 v95, v0
	v_mov_b32_e32 v96, v0
	v_mov_b32_e32 v97, v0
	v_mov_b32_e32 v98, v0
	v_mov_b32_e32 v99, v0
	v_mov_b32_e32 v100, v0
	v_mov_b32_e32 v101, v0
	v_mov_b32_e32 v102, v0
	v_mov_b32_e32 v103, v0
	v_mov_b32_e32 v104, v0
	v_mov_b32_e32 v105, v0
	v_mov_b32_e32 v106, v0
	v_mov_b32_e32 v107, v0
	v_mov_b32_e32 v108, v0
	v_mov_b32_e32 v109, v0
	v_mov_b32_e32 v110, v0
	v_mov_b32_e32 v111, v0
	v_mov_b32_e32 v112, v0
	v_mov_b32_e32 v113, v0
	v_mov_b32_e32 v114, v0
	v_mov_b32_e32 v115, v0
	v_mov_b32_e32 v116, v0
	v_mov_b32_e32 v117, v0
	v_mov_b32_e32 v118, v0
	v_mov_b32_e32 v119, v0
	v_mov_b32_e32 v120, v0
	v_mov_b32_e32 v121, v0
	v_mov_b32_e32 v122, v0
	v_mov_b32_e32 v123, v0
	v_mov_b32_e32 v124, v0
	v_mov_b32_e32 v125, v0
	v_mov_b32_e32 v126, v0
	v_mov_b32_e32 v127, v0
	s_barrier
	.p2align	6

; #define WAIT_V(n) asm volatile("s_waitcnt vmcnt(" #n ")" ::: "memory")
; #define BAR __builtin_amdgcn_s_barrier()
; template <int K, bool SWAP>
; __device__ __forceinline__ void gemm_kloop(const bf16* __restrict__ A, const bf16* __restrict__ Bt,
;                                            f32x4 (&acc)[2][2][4][2], bool pref = false) {
;     ...
;   if (wr == 1) BAR;
;   WAIT_V(4); BAR;
.LBB0_513:
	s_or_b64 exec, exec, s[14:15]
	v_add_u32_e32 v1, v145, v1
	v_and_b32_e32 v1, 0xfffffc00, v1
	v_sub_u32_e32 v1, v145, v1
	v_lshrrev_b32_e32 v4, 4, v1
	v_bitop3_b32 v1, v4, v1, 32 bitop3:0x6c
	v_ashrrev_i32_e32 v5, 31, v1
	v_lshrrev_b32_e32 v5, 26, v5
	v_add_u32_e32 v2, v144, v2
	v_add_u32_e32 v5, v1, v5
	v_ashrrev_i32_e32 v2, 6, v2
	v_ashrrev_i32_e32 v6, 6, v5
	v_and_b32_e32 v5, 0xc0, v5
	v_lshlrev_b32_e32 v4, 3, v2
	v_lshlrev_b32_e32 v2, 5, v2
	v_sub_u32_e32 v1, v1, v5
	v_and_b32_e32 v4, -16, v4
	v_and_b32_e32 v2, 32, v2
	v_ashrrev_i16_sdwa v1, v193, sext(v1) dst_sel:DWORD dst_unused:UNUSED_PAD src0_sel:DWORD src1_sel:BYTE_0
	v_add_u32_e32 v4, v6, v4
	v_add_u32_sdwa v128, v2, sext(v1) dst_sel:DWORD dst_unused:UNUSED_PAD src0_sel:DWORD src1_sel:WORD_0
	v_ashrrev_i32_e32 v1, 31, v0
	v_ashrrev_i32_e32 v5, 31, v4
	v_lshrrev_b32_e32 v1, 22, v1
	v_lshlrev_b64 v[130:131], 11, v[4:5]
	v_ashrrev_i32_e32 v129, 31, v128
	v_readlane_b32 s41, v254, 33
	v_add_u32_e32 v1, v0, v1
	v_lshl_add_u64 v[4:5], s[12:13], 0, v[130:131]
	v_lshlrev_b64 v[6:7], 1, v[128:129]
	v_add_u32_e32 v154, s41, v145
	v_ashrrev_i32_e32 v1, 10, v1
	v_lshl_add_u64 v[4:5], v[4:5], 0, v[6:7]
	s_mov_b64 s[14:15], 0x80
	v_readfirstlane_b32 s7, v154
	v_mul_i32_i24_e32 v2, 0x400, v1
	v_lshl_add_u64 v[4:5], v[4:5], 0, s[14:15]
	s_mov_b32 m0, s7
	v_sub_u32_e32 v2, v0, v2
	s_waitcnt vmcnt(4)
	s_barrier
; #define WAIT_V(n) asm volatile("s_waitcnt vmcnt(" #n ")" ::: "memory")
; #define BAR __builtin_amdgcn_s_barrier()
; template <int K, bool SWAP>
; __device__ __forceinline__ void gemm_kloop(const bf16* __restrict__ A, const bf16* __restrict__ Bt,
;                                            f32x4 (&acc)[2][2][4][2], bool pref = false) {
;     ...
;   int tidx = threadIdx.x;
;   asm volatile("" : "+v"(tidx));
;   const int wid = tidx >> 6, lane = tidx & 63, wr = wid >> 2, wc = wid & 3, fr = lane & 15, fq = lane >> 4;
;   bf16x8 At[4][2], B0[2][2], B1[2][2];
;   constexpr int nt = K / BK;
;   if (!pref) {
;     STAGE(SB(0, 0), Bt, 0, 0); STAGE(SA(0, 0), A, 0, 0);
;     STAGE(SB(0, 1), Bt, HALF, 0); STAGE(SA(0, 1), A, HALF, 0);
;   }
;   if (wr == 1) BAR;
;   WAIT_V(4); BAR;
;   STAGE(SB(1, 0), Bt, 0, 1); STAGE(SA(1, 0), A, 0, 1); STAGE(SB(1, 1), Bt, HALF, 1);
;   WAIT_V(6); BAR;
; __device__ __forceinline__ void zero_acc(f32x4 (&acc)[2][2][4][2]) {
;   _Pragma("unroll") for (int a = 0; a < 2; ++a) _Pragma("unroll") for (int b = 0; b < 2; ++b) _Pragma("unroll") for (int m = 0; m < 4; ++m) _Pragma("unroll") for (int n = 0; n < 2; ++n)
;     acc[a][b][m][n] = f32x4{0.f, 0.f, 0.f, 0.f};
; }
	global_load_lds_dwordx4 v[4:5], off
	v_lshrrev_b32_e32 v4, 4, v2
	v_bitop3_b32 v2, v4, v2, 32 bitop3:0x6c
	v_ashrrev_i32_e32 v5, 31, v2
	v_lshrrev_b32_e32 v5, 26, v5
	v_add_u32_e32 v5, v2, v5
	v_lshlrev_b32_e32 v4, 3, v1
	v_ashrrev_i32_e32 v8, 6, v5
	v_and_b32_e32 v5, 0xc0, v5
	v_and_b32_e32 v4, -16, v4
	v_lshlrev_b32_e32 v1, 5, v1
	v_sub_u32_e32 v2, v2, v5
	v_add_u32_e32 v4, v8, v4
	v_and_b32_e32 v1, 32, v1
	v_ashrrev_i16_sdwa v2, v193, sext(v2) dst_sel:DWORD dst_unused:UNUSED_PAD src0_sel:DWORD src1_sel:BYTE_0
	v_add_u32_sdwa v132, v1, sext(v2) dst_sel:DWORD dst_unused:UNUSED_PAD src0_sel:DWORD src1_sel:WORD_0
	v_ashrrev_i32_e32 v5, 31, v4
	v_lshlrev_b64 v[134:135], 11, v[4:5]
	v_ashrrev_i32_e32 v133, 31, v132
	v_lshl_add_u64 v[4:5], s[12:13], 0, v[134:135]
	v_lshlrev_b64 v[8:9], 1, v[132:133]
	v_add_u32_e32 v1, s41, v0
	v_lshl_add_u64 v[4:5], v[4:5], 0, v[8:9]
	v_readfirstlane_b32 s7, v1
	v_lshl_add_u64 v[4:5], v[4:5], 0, s[14:15]
	s_mov_b32 m0, s7
	v_add_u32_e32 v155, 0x8000, v146
	global_load_lds_dwordx4 v[4:5], off
	v_lshl_add_u64 v[4:5], s[4:5], 0, v[130:131]
	v_lshl_add_u64 v[4:5], v[4:5], 0, v[6:7]
	v_readfirstlane_b32 s7, v155
	v_lshl_add_u64 v[4:5], v[4:5], 0, s[14:15]
	s_mov_b32 m0, s7
	v_add_u32_e32 v156, 0xa000, v146
	global_load_lds_dwordx4 v[4:5], off
	v_lshl_add_u64 v[4:5], s[4:5], 0, v[134:135]
	v_lshl_add_u64 v[4:5], v[4:5], 0, v[8:9]
	v_lshl_add_u64 v[4:5], v[4:5], 0, s[14:15]
	v_readfirstlane_b32 s7, v156
	s_add_u32 s12, s12, 0x40080
	v_readlane_b32 s14, v254, 34
	s_mov_b32 m0, s7
	s_addc_u32 s13, s13, 0
	v_add_u32_e32 v157, s14, v145
	global_load_lds_dwordx4 v[4:5], off
	v_lshl_add_u64 v[4:5], s[12:13], 0, v[130:131]
	v_readfirstlane_b32 s7, v157
	v_lshl_add_u64 v[4:5], v[4:5], 0, v[6:7]
	s_mov_b32 m0, s7
	v_add_u32_e32 v0, s14, v0
	global_load_lds_dwordx4 v[4:5], off
	v_lshl_add_u64 v[4:5], s[12:13], 0, v[134:135]
	v_readfirstlane_b32 s7, v0
	v_lshl_add_u64 v[4:5], v[4:5], 0, v[8:9]
	s_mov_b32 m0, s7
	v_and_b32_e32 v10, 15, v144
	global_load_lds_dwordx4 v[4:5], off
	v_lshlrev_b32_e32 v1, 2, v144
	v_and_b32_e32 v11, 48, v144
	v_lshlrev_b32_e32 v0, 6, v10
	v_and_b32_e32 v1, 32, v1
	s_add_i32 s7, 0, 0x10000
	v_bitop3_b32 v0, v0, v1, v11 bitop3:0x36
	v_lshlrev_b32_e32 v12, 6, v144
	s_movk_i32 s12, 0x3c0
	s_add_u32 s10, s70, s10
	v_add_u32_e32 v2, s7, v0
	v_add_u32_e32 v4, s33, v0
	v_add_u32_e32 v5, s41, v0
	v_add_u32_e32 v10, s14, v0
	v_add_u32_e32 v14, 0, v0
	v_and_or_b32 v0, v12, s12, v11
	s_addc_u32 s11, 0, s11
	v_xad_u32 v11, v0, v1, 0
	v_lshl_add_u64 v[0:1], s[10:11], 0, v[130:131]
	v_lshl_add_u64 v[136:137], v[0:1], 0, v[6:7]
	v_lshl_add_u64 v[0:1], s[10:11], 0, v[134:135]
	v_lshl_add_u64 v[138:139], v[0:1], 0, v[8:9]
	v_lshl_add_u64 v[0:1], s[8:9], 0, v[130:131]
	s_waitcnt vmcnt(6)
	v_lshlrev_b32_e32 v3, 13, v3
	v_lshl_add_u64 v[140:141], v[0:1], 0, v[6:7]
	v_lshl_add_u64 v[0:1], s[8:9], 0, v[134:135]
	v_and_b32_e32 v13, 0x3000, v12
	v_or_b32_e32 v12, 0x800, v3
	v_or_b32_e32 v15, 0x1000, v3
	v_or_b32_e32 v16, 0x1800, v3
	v_lshl_add_u64 v[142:143], v[0:1], 0, v[8:9]
	v_mov_b32_e32 v0, 0
	s_mov_b32 s8, -2
	v_add_u32_e32 v159, v2, v13
	v_add_u32_e32 v151, v14, v3
	v_add_u32_e32 v150, v11, v12
	v_add_u32_e32 v149, v11, v15
	v_add_u32_e32 v148, v11, v16
	v_add_u32_e32 v158, v4, v13
	v_add_u32_e32 v153, v5, v13
	v_add_u32_e32 v152, v10, v13
	v_mov_b32_e32 v1, v0
	v_mov_b32_e32 v2, v0
	v_mov_b32_e32 v3, v0
	v_mov_b32_e32 v4, v0
	v_mov_b32_e32 v5, v0
	v_mov_b32_e32 v6, v0
	v_mov_b32_e32 v7, v0
	v_mov_b32_e32 v8, v0
	v_mov_b32_e32 v9, v0
	v_mov_b32_e32 v10, v0
	v_mov_b32_e32 v11, v0
	v_mov_b32_e32 v12, v0
	v_mov_b32_e32 v13, v0
	v_mov_b32_e32 v14, v0
	v_mov_b32_e32 v15, v0
	v_mov_b32_e32 v16, v0
	v_mov_b32_e32 v17, v0
	v_mov_b32_e32 v18, v0
	v_mov_b32_e32 v19, v0
	v_mov_b32_e32 v20, v0
	v_mov_b32_e32 v21, v0
	v_mov_b32_e32 v22, v0
	v_mov_b32_e32 v23, v0
	v_mov_b32_e32 v24, v0
	v_mov_b32_e32 v25, v0
	v_mov_b32_e32 v26, v0
	v_mov_b32_e32 v27, v0
	v_mov_b32_e32 v28, v0
	v_mov_b32_e32 v29, v0
	v_mov_b32_e32 v30, v0
	v_mov_b32_e32 v31, v0
	v_mov_b32_e32 v32, v0
	v_mov_b32_e32 v33, v0
	v_mov_b32_e32 v34, v0
	v_mov_b32_e32 v35, v0
	v_mov_b32_e32 v36, v0
	v_mov_b32_e32 v37, v0
	v_mov_b32_e32 v38, v0
	v_mov_b32_e32 v39, v0
	v_mov_b32_e32 v40, v0
	v_mov_b32_e32 v41, v0
	v_mov_b32_e32 v42, v0
	v_mov_b32_e32 v43, v0
	v_mov_b32_e32 v44, v0
	v_mov_b32_e32 v45, v0
	v_mov_b32_e32 v46, v0
	v_mov_b32_e32 v47, v0
	v_mov_b32_e32 v48, v0
	v_mov_b32_e32 v49, v0
	v_mov_b32_e32 v50, v0
	v_mov_b32_e32 v51, v0
	v_mov_b32_e32 v52, v0
	v_mov_b32_e32 v53, v0
	v_mov_b32_e32 v54, v0
	v_mov_b32_e32 v55, v0
	v_mov_b32_e32 v56, v0
	v_mov_b32_e32 v57, v0
	v_mov_b32_e32 v58, v0
	v_mov_b32_e32 v59, v0
	v_mov_b32_e32 v60, v0
	v_mov_b32_e32 v61, v0
	v_mov_b32_e32 v62, v0
	v_mov_b32_e32 v63, v0
	v_mov_b32_e32 v72, v0
	v_mov_b32_e32 v73, v0
	v_mov_b32_e32 v74, v0
	v_mov_b32_e32 v75, v0
	v_mov_b32_e32 v84, v0
	v_mov_b32_e32 v85, v0
	v_mov_b32_e32 v86, v0
	v_mov_b32_e32 v87, v0
	v_mov_b32_e32 v88, v0
	v_mov_b32_e32 v89, v0
	v_mov_b32_e32 v90, v0
	v_mov_b32_e32 v91, v0
	v_mov_b32_e32 v92, v0
	v_mov_b32_e32 v93, v0
	v_mov_b32_e32 v94, v0
	v_mov_b32_e32 v95, v0
	v_mov_b32_e32 v96, v0
	v_mov_b32_e32 v97, v0
	v_mov_b32_e32 v98, v0
	v_mov_b32_e32 v99, v0
	v_mov_b32_e32 v100, v0
	v_mov_b32_e32 v101, v0
	v_mov_b32_e32 v102, v0
	v_mov_b32_e32 v103, v0
	v_mov_b32_e32 v104, v0
	v_mov_b32_e32 v105, v0
	v_mov_b32_e32 v106, v0
	v_mov_b32_e32 v107, v0
	v_mov_b32_e32 v108, v0
	v_mov_b32_e32 v109, v0
	v_mov_b32_e32 v110, v0
	v_mov_b32_e32 v111, v0
	v_mov_b32_e32 v112, v0
	v_mov_b32_e32 v113, v0
	v_mov_b32_e32 v114, v0
	v_mov_b32_e32 v115, v0
	v_mov_b32_e32 v116, v0
	v_mov_b32_e32 v117, v0
	v_mov_b32_e32 v118, v0
	v_mov_b32_e32 v119, v0
	v_mov_b32_e32 v120, v0
	v_mov_b32_e32 v121, v0
	v_mov_b32_e32 v122, v0
	v_mov_b32_e32 v123, v0
	v_mov_b32_e32 v124, v0
	v_mov_b32_e32 v125, v0
	v_mov_b32_e32 v126, v0
	v_mov_b32_e32 v127, v0
	v_mov_b32_e32 v64, v0
	v_mov_b32_e32 v65, v0
	v_mov_b32_e32 v66, v0
	v_mov_b32_e32 v67, v0
	v_mov_b32_e32 v68, v0
	v_mov_b32_e32 v69, v0
	v_mov_b32_e32 v70, v0
	v_mov_b32_e32 v71, v0
	v_mov_b32_e32 v76, v0
	v_mov_b32_e32 v77, v0
	v_mov_b32_e32 v78, v0
	v_mov_b32_e32 v79, v0
	v_mov_b32_e32 v80, v0
	v_mov_b32_e32 v81, v0
	v_mov_b32_e32 v82, v0
	v_mov_b32_e32 v83, v0
	s_barrier
	.p2align	6

; #define WAIT_V(n) asm volatile("s_waitcnt vmcnt(" #n ")" ::: "memory")
; #define BAR __builtin_amdgcn_s_barrier()
; template <int K, bool SWAP>
; __device__ __forceinline__ void gemm_kloop(const bf16* __restrict__ A, const bf16* __restrict__ Bt,
;                                            f32x4 (&acc)[2][2][4][2], bool pref = false) {
;     ...
;   if (wr == 1) BAR;
;   WAIT_V(4); BAR;
.LBB0_526:
	s_or_b64 exec, exec, s[14:15]
	v_add_u32_e32 v1, v145, v1
	v_and_b32_e32 v1, 0xfffffc00, v1
	v_sub_u32_e32 v1, v145, v1
	v_lshrrev_b32_e32 v4, 4, v1
	v_bitop3_b32 v1, v4, v1, 32 bitop3:0x6c
	v_ashrrev_i32_e32 v5, 31, v1
	v_lshrrev_b32_e32 v5, 26, v5
	v_add_u32_e32 v2, v144, v2
	v_add_u32_e32 v5, v1, v5
	v_ashrrev_i32_e32 v2, 6, v2
	v_ashrrev_i32_e32 v6, 6, v5
	v_and_b32_e32 v5, 0xc0, v5
	v_lshlrev_b32_e32 v4, 3, v2
	v_lshlrev_b32_e32 v2, 5, v2
	v_sub_u32_e32 v1, v1, v5
	v_and_b32_e32 v4, -16, v4
	v_and_b32_e32 v2, 32, v2
	v_ashrrev_i16_sdwa v1, v193, sext(v1) dst_sel:DWORD dst_unused:UNUSED_PAD src0_sel:DWORD src1_sel:BYTE_0
	v_add_u32_e32 v4, v6, v4
	v_add_u32_sdwa v128, v2, sext(v1) dst_sel:DWORD dst_unused:UNUSED_PAD src0_sel:DWORD src1_sel:WORD_0
	v_ashrrev_i32_e32 v1, 31, v0
	v_ashrrev_i32_e32 v5, 31, v4
	v_lshrrev_b32_e32 v1, 22, v1
	v_lshlrev_b64 v[130:131], 11, v[4:5]
	v_ashrrev_i32_e32 v129, 31, v128
	v_readlane_b32 s41, v254, 33
	v_add_u32_e32 v1, v0, v1
	v_lshl_add_u64 v[4:5], s[12:13], 0, v[130:131]
	v_lshlrev_b64 v[6:7], 1, v[128:129]
	v_add_u32_e32 v154, s41, v145
	v_ashrrev_i32_e32 v1, 10, v1
	v_lshl_add_u64 v[4:5], v[4:5], 0, v[6:7]
	s_mov_b64 s[14:15], 0x80
	v_readfirstlane_b32 s7, v154
	v_mul_i32_i24_e32 v2, 0x400, v1
	v_lshl_add_u64 v[4:5], v[4:5], 0, s[14:15]
	s_mov_b32 m0, s7
	v_sub_u32_e32 v2, v0, v2
	s_waitcnt vmcnt(4)
	s_barrier
; #define WAIT_V(n) asm volatile("s_waitcnt vmcnt(" #n ")" ::: "memory")
; #define BAR __builtin_amdgcn_s_barrier()
; template <int K, bool SWAP>
; __device__ __forceinline__ void gemm_kloop(const bf16* __restrict__ A, const bf16* __restrict__ Bt,
;                                            f32x4 (&acc)[2][2][4][2], bool pref = false) {
;     ...
;   int tidx = threadIdx.x;
;   asm volatile("" : "+v"(tidx));
;   const int wid = tidx >> 6, lane = tidx & 63, wr = wid >> 2, wc = wid & 3, fr = lane & 15, fq = lane >> 4;
;   bf16x8 At[4][2], B0[2][2], B1[2][2];
;   constexpr int nt = K / BK;
;   if (!pref) {
;     STAGE(SB(0, 0), Bt, 0, 0); STAGE(SA(0, 0), A, 0, 0);
;     STAGE(SB(0, 1), Bt, HALF, 0); STAGE(SA(0, 1), A, HALF, 0);
;   }
;   if (wr == 1) BAR;
;   WAIT_V(4); BAR;
;   STAGE(SB(1, 0), Bt, 0, 1); STAGE(SA(1, 0), A, 0, 1); STAGE(SB(1, 1), Bt, HALF, 1);
;   WAIT_V(6); BAR;
; __device__ __forceinline__ void zero_acc(f32x4 (&acc)[2][2][4][2]) {
;   _Pragma("unroll") for (int a = 0; a < 2; ++a) _Pragma("unroll") for (int b = 0; b < 2; ++b) _Pragma("unroll") for (int m = 0; m < 4; ++m) _Pragma("unroll") for (int n = 0; n < 2; ++n)
;     acc[a][b][m][n] = f32x4{0.f, 0.f, 0.f, 0.f};
; }
	global_load_lds_dwordx4 v[4:5], off
	v_lshrrev_b32_e32 v4, 4, v2
	v_bitop3_b32 v2, v4, v2, 32 bitop3:0x6c
	v_ashrrev_i32_e32 v5, 31, v2
	v_lshrrev_b32_e32 v5, 26, v5
	v_add_u32_e32 v5, v2, v5
	v_lshlrev_b32_e32 v4, 3, v1
	v_ashrrev_i32_e32 v8, 6, v5
	v_and_b32_e32 v5, 0xc0, v5
	v_and_b32_e32 v4, -16, v4
	v_lshlrev_b32_e32 v1, 5, v1
	v_sub_u32_e32 v2, v2, v5
	v_add_u32_e32 v4, v8, v4
	v_and_b32_e32 v1, 32, v1
	v_ashrrev_i16_sdwa v2, v193, sext(v2) dst_sel:DWORD dst_unused:UNUSED_PAD src0_sel:DWORD src1_sel:BYTE_0
	v_add_u32_sdwa v132, v1, sext(v2) dst_sel:DWORD dst_unused:UNUSED_PAD src0_sel:DWORD src1_sel:WORD_0
	v_ashrrev_i32_e32 v5, 31, v4
	v_lshlrev_b64 v[134:135], 11, v[4:5]
	v_ashrrev_i32_e32 v133, 31, v132
	v_lshl_add_u64 v[4:5], s[12:13], 0, v[134:135]
	v_lshlrev_b64 v[8:9], 1, v[132:133]
	v_add_u32_e32 v1, s41, v0
	v_lshl_add_u64 v[4:5], v[4:5], 0, v[8:9]
	v_readfirstlane_b32 s7, v1
	v_lshl_add_u64 v[4:5], v[4:5], 0, s[14:15]
	s_mov_b32 m0, s7
	v_add_u32_e32 v155, 0x8000, v146
	global_load_lds_dwordx4 v[4:5], off
	v_lshl_add_u64 v[4:5], s[0:1], 0, v[130:131]
	v_lshl_add_u64 v[4:5], v[4:5], 0, v[6:7]
	v_readfirstlane_b32 s7, v155
	v_lshl_add_u64 v[4:5], v[4:5], 0, s[14:15]
	s_mov_b32 m0, s7
	v_add_u32_e32 v156, 0xa000, v146
	global_load_lds_dwordx4 v[4:5], off
	v_lshl_add_u64 v[4:5], s[0:1], 0, v[134:135]
	v_lshl_add_u64 v[4:5], v[4:5], 0, v[8:9]
	v_lshl_add_u64 v[4:5], v[4:5], 0, s[14:15]
	v_readfirstlane_b32 s7, v156
	s_add_u32 s12, s12, 0x40080
	v_readlane_b32 s14, v254, 34
	s_mov_b32 m0, s7
	s_addc_u32 s13, s13, 0
	v_add_u32_e32 v157, s14, v145
	global_load_lds_dwordx4 v[4:5], off
	v_lshl_add_u64 v[4:5], s[12:13], 0, v[130:131]
	v_readfirstlane_b32 s7, v157
	v_lshl_add_u64 v[4:5], v[4:5], 0, v[6:7]
	s_mov_b32 m0, s7
	v_add_u32_e32 v0, s14, v0
	global_load_lds_dwordx4 v[4:5], off
	v_lshl_add_u64 v[4:5], s[12:13], 0, v[134:135]
	v_readfirstlane_b32 s7, v0
	v_lshl_add_u64 v[4:5], v[4:5], 0, v[8:9]
	s_mov_b32 m0, s7
	v_and_b32_e32 v10, 15, v144
	global_load_lds_dwordx4 v[4:5], off
	v_lshlrev_b32_e32 v1, 2, v144
	v_and_b32_e32 v11, 48, v144
	v_lshlrev_b32_e32 v0, 6, v10
	v_and_b32_e32 v1, 32, v1
	s_add_i32 s7, 0, 0x10000
	v_bitop3_b32 v0, v0, v1, v11 bitop3:0x36
	v_lshlrev_b32_e32 v12, 6, v144
	s_movk_i32 s12, 0x3c0
	s_add_u32 s10, s70, s10
	v_add_u32_e32 v2, s7, v0
	v_add_u32_e32 v4, s33, v0
	v_add_u32_e32 v5, s41, v0
	v_add_u32_e32 v10, s14, v0
	v_add_u32_e32 v14, 0, v0
	v_and_or_b32 v0, v12, s12, v11
	s_addc_u32 s11, 0, s11
	v_xad_u32 v11, v0, v1, 0
	v_lshl_add_u64 v[0:1], s[10:11], 0, v[130:131]
	v_lshl_add_u64 v[136:137], v[0:1], 0, v[6:7]
	v_lshl_add_u64 v[0:1], s[10:11], 0, v[134:135]
	v_lshl_add_u64 v[138:139], v[0:1], 0, v[8:9]
	v_lshl_add_u64 v[0:1], s[8:9], 0, v[130:131]
	s_waitcnt vmcnt(6)
	v_lshlrev_b32_e32 v3, 13, v3
	v_lshl_add_u64 v[140:141], v[0:1], 0, v[6:7]
	v_lshl_add_u64 v[0:1], s[8:9], 0, v[134:135]
	v_and_b32_e32 v13, 0x3000, v12
	v_or_b32_e32 v12, 0x800, v3
	v_or_b32_e32 v15, 0x1000, v3
	v_or_b32_e32 v16, 0x1800, v3
	v_lshl_add_u64 v[142:143], v[0:1], 0, v[8:9]
	v_mov_b32_e32 v0, 0
	s_mov_b32 s8, -2
	v_add_u32_e32 v159, v2, v13
	v_add_u32_e32 v151, v14, v3
	v_add_u32_e32 v150, v11, v12
	v_add_u32_e32 v149, v11, v15
	v_add_u32_e32 v148, v11, v16
	v_add_u32_e32 v158, v4, v13
	v_add_u32_e32 v153, v5, v13
	v_add_u32_e32 v152, v10, v13
	v_mov_b32_e32 v1, v0
	v_mov_b32_e32 v2, v0
	v_mov_b32_e32 v3, v0
	v_mov_b32_e32 v4, v0
	v_mov_b32_e32 v5, v0
	v_mov_b32_e32 v6, v0
	v_mov_b32_e32 v7, v0
	v_mov_b32_e32 v8, v0
	v_mov_b32_e32 v9, v0
	v_mov_b32_e32 v10, v0
	v_mov_b32_e32 v11, v0
	v_mov_b32_e32 v12, v0
	v_mov_b32_e32 v13, v0
	v_mov_b32_e32 v14, v0
	v_mov_b32_e32 v15, v0
	v_mov_b32_e32 v16, v0
	v_mov_b32_e32 v17, v0
	v_mov_b32_e32 v18, v0
	v_mov_b32_e32 v19, v0
	v_mov_b32_e32 v20, v0
	v_mov_b32_e32 v21, v0
	v_mov_b32_e32 v22, v0
	v_mov_b32_e32 v23, v0
	v_mov_b32_e32 v24, v0
	v_mov_b32_e32 v25, v0
	v_mov_b32_e32 v26, v0
	v_mov_b32_e32 v27, v0
	v_mov_b32_e32 v28, v0
	v_mov_b32_e32 v29, v0
	v_mov_b32_e32 v30, v0
	v_mov_b32_e32 v31, v0
	v_mov_b32_e32 v32, v0
	v_mov_b32_e32 v33, v0
	v_mov_b32_e32 v34, v0
	v_mov_b32_e32 v35, v0
	v_mov_b32_e32 v36, v0
	v_mov_b32_e32 v37, v0
	v_mov_b32_e32 v38, v0
	v_mov_b32_e32 v39, v0
	v_mov_b32_e32 v40, v0
	v_mov_b32_e32 v41, v0
	v_mov_b32_e32 v42, v0
	v_mov_b32_e32 v43, v0
	v_mov_b32_e32 v44, v0
	v_mov_b32_e32 v45, v0
	v_mov_b32_e32 v46, v0
	v_mov_b32_e32 v47, v0
	v_mov_b32_e32 v48, v0
	v_mov_b32_e32 v49, v0
	v_mov_b32_e32 v50, v0
	v_mov_b32_e32 v51, v0
	v_mov_b32_e32 v52, v0
	v_mov_b32_e32 v53, v0
	v_mov_b32_e32 v54, v0
	v_mov_b32_e32 v55, v0
	v_mov_b32_e32 v56, v0
	v_mov_b32_e32 v57, v0
	v_mov_b32_e32 v58, v0
	v_mov_b32_e32 v59, v0
	v_mov_b32_e32 v60, v0
	v_mov_b32_e32 v61, v0
	v_mov_b32_e32 v62, v0
	v_mov_b32_e32 v63, v0
	v_mov_b32_e32 v64, v0
	v_mov_b32_e32 v65, v0
	v_mov_b32_e32 v66, v0
	v_mov_b32_e32 v67, v0
	v_mov_b32_e32 v68, v0
	v_mov_b32_e32 v69, v0
	v_mov_b32_e32 v70, v0
	v_mov_b32_e32 v71, v0
	v_mov_b32_e32 v72, v0
	v_mov_b32_e32 v73, v0
	v_mov_b32_e32 v74, v0
	v_mov_b32_e32 v75, v0
	v_mov_b32_e32 v76, v0
	v_mov_b32_e32 v77, v0
	v_mov_b32_e32 v78, v0
	v_mov_b32_e32 v79, v0
	v_mov_b32_e32 v80, v0
	v_mov_b32_e32 v81, v0
	v_mov_b32_e32 v82, v0
	v_mov_b32_e32 v83, v0
	v_mov_b32_e32 v84, v0
	v_mov_b32_e32 v85, v0
	v_mov_b32_e32 v86, v0
	v_mov_b32_e32 v87, v0
	v_mov_b32_e32 v88, v0
	v_mov_b32_e32 v89, v0
	v_mov_b32_e32 v90, v0
	v_mov_b32_e32 v91, v0
	v_mov_b32_e32 v92, v0
	v_mov_b32_e32 v93, v0
	v_mov_b32_e32 v94, v0
	v_mov_b32_e32 v95, v0
	v_mov_b32_e32 v96, v0
	v_mov_b32_e32 v97, v0
	v_mov_b32_e32 v98, v0
	v_mov_b32_e32 v99, v0
	v_mov_b32_e32 v100, v0
	v_mov_b32_e32 v101, v0
	v_mov_b32_e32 v102, v0
	v_mov_b32_e32 v103, v0
	v_mov_b32_e32 v104, v0
	v_mov_b32_e32 v105, v0
	v_mov_b32_e32 v106, v0
	v_mov_b32_e32 v107, v0
	v_mov_b32_e32 v108, v0
	v_mov_b32_e32 v109, v0
	v_mov_b32_e32 v110, v0
	v_mov_b32_e32 v111, v0
	v_mov_b32_e32 v112, v0
	v_mov_b32_e32 v113, v0
	v_mov_b32_e32 v114, v0
	v_mov_b32_e32 v115, v0
	v_mov_b32_e32 v116, v0
	v_mov_b32_e32 v117, v0
	v_mov_b32_e32 v118, v0
	v_mov_b32_e32 v119, v0
	v_mov_b32_e32 v120, v0
	v_mov_b32_e32 v121, v0
	v_mov_b32_e32 v122, v0
	v_mov_b32_e32 v123, v0
	v_mov_b32_e32 v124, v0
	v_mov_b32_e32 v125, v0
	v_mov_b32_e32 v126, v0
	v_mov_b32_e32 v127, v0
	s_barrier
	.p2align	6

; #define WAIT_V(n) asm volatile("s_waitcnt vmcnt(" #n ")" ::: "memory")
; #define BAR __builtin_amdgcn_s_barrier()
; template <int K, bool SWAP>
; __device__ __forceinline__ void gemm_kloop(const bf16* __restrict__ A, const bf16* __restrict__ Bt,
;                                            f32x4 (&acc)[2][2][4][2], bool pref = false) {
;     ...
;   if (wr == 1) BAR;
;   WAIT_V(4); BAR;
.LBB0_541:
	s_or_b64 exec, exec, s[10:11]
	v_add_u32_e32 v1, v145, v1
	v_and_b32_e32 v1, 0xfffffc00, v1
	v_sub_u32_e32 v1, v145, v1
	v_lshrrev_b32_e32 v4, 4, v1
	v_bitop3_b32 v1, v4, v1, 32 bitop3:0x6c
	v_ashrrev_i32_e32 v5, 31, v1
	v_lshrrev_b32_e32 v5, 26, v5
	v_add_u32_e32 v2, v144, v2
	v_add_u32_e32 v5, v1, v5
	v_ashrrev_i32_e32 v2, 6, v2
	v_ashrrev_i32_e32 v6, 6, v5
	v_and_b32_e32 v5, 0xc0, v5
	v_lshlrev_b32_e32 v4, 3, v2
	v_lshlrev_b32_e32 v2, 5, v2
	v_sub_u32_e32 v1, v1, v5
	v_and_b32_e32 v4, -16, v4
	v_and_b32_e32 v2, 32, v2
	v_ashrrev_i16_sdwa v1, v193, sext(v1) dst_sel:DWORD dst_unused:UNUSED_PAD src0_sel:DWORD src1_sel:BYTE_0
	v_add_u32_e32 v4, v6, v4
	v_add_u32_sdwa v128, v2, sext(v1) dst_sel:DWORD dst_unused:UNUSED_PAD src0_sel:DWORD src1_sel:WORD_0
	v_ashrrev_i32_e32 v1, 31, v0
	v_ashrrev_i32_e32 v5, 31, v4
	v_lshrrev_b32_e32 v1, 22, v1
	v_lshlrev_b64 v[130:131], 11, v[4:5]
	v_ashrrev_i32_e32 v129, 31, v128
	v_readlane_b32 s11, v254, 33
	v_add_u32_e32 v1, v0, v1
	v_lshl_add_u64 v[4:5], s[8:9], 0, v[130:131]
	v_lshlrev_b64 v[6:7], 1, v[128:129]
	v_add_u32_e32 v154, s11, v145
	v_ashrrev_i32_e32 v1, 10, v1
	v_lshl_add_u64 v[4:5], v[4:5], 0, v[6:7]
	s_mov_b64 s[60:61], 0x80
	v_readfirstlane_b32 s10, v154
	v_mul_i32_i24_e32 v2, 0x400, v1
	v_lshl_add_u64 v[4:5], v[4:5], 0, s[60:61]
	s_mov_b32 m0, s10
	v_sub_u32_e32 v2, v0, v2
	s_waitcnt vmcnt(4)
	s_barrier
; #define WAIT_V(n) asm volatile("s_waitcnt vmcnt(" #n ")" ::: "memory")
; #define BAR __builtin_amdgcn_s_barrier()
; template <int K, bool SWAP>
; __device__ __forceinline__ void gemm_kloop(const bf16* __restrict__ A, const bf16* __restrict__ Bt,
;                                            f32x4 (&acc)[2][2][4][2], bool pref = false) {
;     ...
;   int tidx = threadIdx.x;
;   asm volatile("" : "+v"(tidx));
;   const int wid = tidx >> 6, lane = tidx & 63, wr = wid >> 2, wc = wid & 3, fr = lane & 15, fq = lane >> 4;
;   bf16x8 At[4][2], B0[2][2], B1[2][2];
;   constexpr int nt = K / BK;
;   if (!pref) {
;     STAGE(SB(0, 0), Bt, 0, 0); STAGE(SA(0, 0), A, 0, 0);
;     STAGE(SB(0, 1), Bt, HALF, 0); STAGE(SA(0, 1), A, HALF, 0);
;   }
;   if (wr == 1) BAR;
;   WAIT_V(4); BAR;
;   STAGE(SB(1, 0), Bt, 0, 1); STAGE(SA(1, 0), A, 0, 1); STAGE(SB(1, 1), Bt, HALF, 1);
;   WAIT_V(6); BAR;
; __device__ __forceinline__ void zero_acc(f32x4 (&acc)[2][2][4][2]) {
;   _Pragma("unroll") for (int a = 0; a < 2; ++a) _Pragma("unroll") for (int b = 0; b < 2; ++b) _Pragma("unroll") for (int m = 0; m < 4; ++m) _Pragma("unroll") for (int n = 0; n < 2; ++n)
;     acc[a][b][m][n] = f32x4{0.f, 0.f, 0.f, 0.f};
; }
	global_load_lds_dwordx4 v[4:5], off
	v_lshrrev_b32_e32 v4, 4, v2
	v_bitop3_b32 v2, v4, v2, 32 bitop3:0x6c
	v_ashrrev_i32_e32 v5, 31, v2
	v_lshrrev_b32_e32 v5, 26, v5
	v_add_u32_e32 v5, v2, v5
	v_lshlrev_b32_e32 v4, 3, v1
	v_ashrrev_i32_e32 v8, 6, v5
	v_and_b32_e32 v5, 0xc0, v5
	v_and_b32_e32 v4, -16, v4
	v_lshlrev_b32_e32 v1, 5, v1
	v_sub_u32_e32 v2, v2, v5
	v_add_u32_e32 v4, v8, v4
	v_and_b32_e32 v1, 32, v1
	v_ashrrev_i16_sdwa v2, v193, sext(v2) dst_sel:DWORD dst_unused:UNUSED_PAD src0_sel:DWORD src1_sel:BYTE_0
	v_add_u32_sdwa v132, v1, sext(v2) dst_sel:DWORD dst_unused:UNUSED_PAD src0_sel:DWORD src1_sel:WORD_0
	v_ashrrev_i32_e32 v5, 31, v4
	v_lshlrev_b64 v[134:135], 11, v[4:5]
	v_ashrrev_i32_e32 v133, 31, v132
	v_lshl_add_u64 v[4:5], s[8:9], 0, v[134:135]
	v_lshlrev_b64 v[8:9], 1, v[132:133]
	v_add_u32_e32 v1, s11, v0
	v_lshl_add_u64 v[4:5], v[4:5], 0, v[8:9]
	v_readfirstlane_b32 s10, v1
	v_lshl_add_u64 v[4:5], v[4:5], 0, s[60:61]
	s_mov_b32 m0, s10
	v_add_u32_e32 v155, 0x8000, v146
	global_load_lds_dwordx4 v[4:5], off
	v_lshl_add_u64 v[4:5], s[0:1], 0, v[130:131]
	v_lshl_add_u64 v[4:5], v[4:5], 0, v[6:7]
	v_readfirstlane_b32 s10, v155
	v_lshl_add_u64 v[4:5], v[4:5], 0, s[60:61]
	s_mov_b32 m0, s10
	v_add_u32_e32 v156, 0xa000, v146
	global_load_lds_dwordx4 v[4:5], off
	v_lshl_add_u64 v[4:5], s[0:1], 0, v[134:135]
	v_lshl_add_u64 v[4:5], v[4:5], 0, v[8:9]
	v_readfirstlane_b32 s10, v156
	s_add_u32 s8, s8, 0x40080
	v_readlane_b32 s41, v254, 34
	v_lshl_add_u64 v[4:5], v[4:5], 0, s[60:61]
	s_mov_b32 m0, s10
	s_addc_u32 s9, s9, 0
	v_add_u32_e32 v157, s41, v145
	global_load_lds_dwordx4 v[4:5], off
	v_lshl_add_u64 v[4:5], s[8:9], 0, v[130:131]
	v_readfirstlane_b32 s10, v157
	v_lshl_add_u64 v[4:5], v[4:5], 0, v[6:7]
	s_mov_b32 m0, s10
	v_add_u32_e32 v0, s41, v0
	global_load_lds_dwordx4 v[4:5], off
	v_lshl_add_u64 v[4:5], s[8:9], 0, v[134:135]
	v_readfirstlane_b32 s8, v0
	v_lshl_add_u64 v[4:5], v[4:5], 0, v[8:9]
	s_mov_b32 m0, s8
	v_and_b32_e32 v10, 15, v144
	global_load_lds_dwordx4 v[4:5], off
	v_lshlrev_b32_e32 v1, 2, v144
	v_and_b32_e32 v11, 48, v144
	v_lshlrev_b32_e32 v0, 6, v10
	v_and_b32_e32 v1, 32, v1
	s_add_i32 s8, 0, 0x10000
	v_bitop3_b32 v0, v0, v1, v11 bitop3:0x36
	v_lshlrev_b32_e32 v12, 6, v144
	s_movk_i32 s9, 0x3c0
	s_add_u32 s6, s70, s6
	v_add_u32_e32 v2, s8, v0
	v_add_u32_e32 v4, s33, v0
	v_add_u32_e32 v5, s11, v0
	v_add_u32_e32 v10, s41, v0
	v_add_u32_e32 v14, 0, v0
	v_and_or_b32 v0, v12, s9, v11
	s_addc_u32 s7, 0, s7
	v_xad_u32 v11, v0, v1, 0
	v_lshl_add_u64 v[0:1], s[6:7], 0, v[130:131]
	v_lshl_add_u64 v[136:137], v[0:1], 0, v[6:7]
	v_lshl_add_u64 v[0:1], s[6:7], 0, v[134:135]
	v_lshl_add_u64 v[138:139], v[0:1], 0, v[8:9]
	v_lshl_add_u64 v[0:1], s[4:5], 0, v[130:131]
	s_waitcnt vmcnt(6)
	v_lshlrev_b32_e32 v3, 13, v3
	v_lshl_add_u64 v[140:141], v[0:1], 0, v[6:7]
	v_lshl_add_u64 v[0:1], s[4:5], 0, v[134:135]
	v_and_b32_e32 v13, 0x3000, v12
	v_or_b32_e32 v12, 0x800, v3
	v_or_b32_e32 v15, 0x1000, v3
	v_or_b32_e32 v16, 0x1800, v3
	v_lshl_add_u64 v[142:143], v[0:1], 0, v[8:9]
	v_mov_b32_e32 v0, 0
	s_mov_b32 s4, -2
	v_add_u32_e32 v159, v2, v13
	v_add_u32_e32 v151, v14, v3
	v_add_u32_e32 v150, v11, v12
	v_add_u32_e32 v149, v11, v15
	v_add_u32_e32 v148, v11, v16
	v_add_u32_e32 v158, v4, v13
	v_add_u32_e32 v153, v5, v13
	v_add_u32_e32 v152, v10, v13
	v_mov_b32_e32 v1, v0
	v_mov_b32_e32 v2, v0
	v_mov_b32_e32 v3, v0
	v_mov_b32_e32 v4, v0
	v_mov_b32_e32 v5, v0
	v_mov_b32_e32 v6, v0
	v_mov_b32_e32 v7, v0
	v_mov_b32_e32 v8, v0
	v_mov_b32_e32 v9, v0
	v_mov_b32_e32 v10, v0
	v_mov_b32_e32 v11, v0
	v_mov_b32_e32 v12, v0
	v_mov_b32_e32 v13, v0
	v_mov_b32_e32 v14, v0
	v_mov_b32_e32 v15, v0
	v_mov_b32_e32 v16, v0
	v_mov_b32_e32 v17, v0
	v_mov_b32_e32 v18, v0
	v_mov_b32_e32 v19, v0
	v_mov_b32_e32 v20, v0
	v_mov_b32_e32 v21, v0
	v_mov_b32_e32 v22, v0
	v_mov_b32_e32 v23, v0
	v_mov_b32_e32 v24, v0
	v_mov_b32_e32 v25, v0
	v_mov_b32_e32 v26, v0
	v_mov_b32_e32 v27, v0
	v_mov_b32_e32 v28, v0
	v_mov_b32_e32 v29, v0
	v_mov_b32_e32 v30, v0
	v_mov_b32_e32 v31, v0
	v_mov_b32_e32 v32, v0
	v_mov_b32_e32 v33, v0
	v_mov_b32_e32 v34, v0
	v_mov_b32_e32 v35, v0
	v_mov_b32_e32 v36, v0
	v_mov_b32_e32 v37, v0
	v_mov_b32_e32 v38, v0
	v_mov_b32_e32 v39, v0
	v_mov_b32_e32 v40, v0
	v_mov_b32_e32 v41, v0
	v_mov_b32_e32 v42, v0
	v_mov_b32_e32 v43, v0
	v_mov_b32_e32 v44, v0
	v_mov_b32_e32 v45, v0
	v_mov_b32_e32 v46, v0
	v_mov_b32_e32 v47, v0
	v_mov_b32_e32 v48, v0
	v_mov_b32_e32 v49, v0
	v_mov_b32_e32 v50, v0
	v_mov_b32_e32 v51, v0
	v_mov_b32_e32 v52, v0
	v_mov_b32_e32 v53, v0
	v_mov_b32_e32 v54, v0
	v_mov_b32_e32 v55, v0
	v_mov_b32_e32 v56, v0
	v_mov_b32_e32 v57, v0
	v_mov_b32_e32 v58, v0
	v_mov_b32_e32 v59, v0
	v_mov_b32_e32 v60, v0
	v_mov_b32_e32 v61, v0
	v_mov_b32_e32 v62, v0
	v_mov_b32_e32 v63, v0
	v_mov_b32_e32 v64, v0
	v_mov_b32_e32 v65, v0
	v_mov_b32_e32 v66, v0
	v_mov_b32_e32 v67, v0
	v_mov_b32_e32 v68, v0
	v_mov_b32_e32 v69, v0
	v_mov_b32_e32 v70, v0
	v_mov_b32_e32 v71, v0
	v_mov_b32_e32 v72, v0
	v_mov_b32_e32 v73, v0
	v_mov_b32_e32 v74, v0
	v_mov_b32_e32 v75, v0
	v_mov_b32_e32 v76, v0
	v_mov_b32_e32 v77, v0
	v_mov_b32_e32 v78, v0
	v_mov_b32_e32 v79, v0
	v_mov_b32_e32 v80, v0
	v_mov_b32_e32 v81, v0
	v_mov_b32_e32 v82, v0
	v_mov_b32_e32 v83, v0
	v_mov_b32_e32 v84, v0
	v_mov_b32_e32 v85, v0
	v_mov_b32_e32 v86, v0
	v_mov_b32_e32 v87, v0
	v_mov_b32_e32 v88, v0
	v_mov_b32_e32 v89, v0
	v_mov_b32_e32 v90, v0
	v_mov_b32_e32 v91, v0
	v_mov_b32_e32 v92, v0
	v_mov_b32_e32 v93, v0
	v_mov_b32_e32 v94, v0
	v_mov_b32_e32 v95, v0
	v_mov_b32_e32 v96, v0
	v_mov_b32_e32 v97, v0
	v_mov_b32_e32 v98, v0
	v_mov_b32_e32 v99, v0
	v_mov_b32_e32 v100, v0
	v_mov_b32_e32 v101, v0
	v_mov_b32_e32 v102, v0
	v_mov_b32_e32 v103, v0
	v_mov_b32_e32 v104, v0
	v_mov_b32_e32 v105, v0
	v_mov_b32_e32 v106, v0
	v_mov_b32_e32 v107, v0
	v_mov_b32_e32 v108, v0
	v_mov_b32_e32 v109, v0
	v_mov_b32_e32 v110, v0
	v_mov_b32_e32 v111, v0
	v_mov_b32_e32 v112, v0
	v_mov_b32_e32 v113, v0
	v_mov_b32_e32 v114, v0
	v_mov_b32_e32 v115, v0
	v_mov_b32_e32 v116, v0
	v_mov_b32_e32 v117, v0
	v_mov_b32_e32 v118, v0
	v_mov_b32_e32 v119, v0
	v_mov_b32_e32 v120, v0
	v_mov_b32_e32 v121, v0
	v_mov_b32_e32 v122, v0
	v_mov_b32_e32 v123, v0
	v_mov_b32_e32 v124, v0
	v_mov_b32_e32 v125, v0
	v_mov_b32_e32 v126, v0
	v_mov_b32_e32 v127, v0
	s_barrier
	.p2align	6

; #define WAIT_V(n) asm volatile("s_waitcnt vmcnt(" #n ")" ::: "memory")
; #define BAR __builtin_amdgcn_s_barrier()
; template <int K, bool SWAP>
; __device__ __forceinline__ void gemm_kloop(const bf16* __restrict__ A, const bf16* __restrict__ Bt,
;                                            f32x4 (&acc)[2][2][4][2], bool pref = false) {
;     ...
;   if (wr == 1) BAR;
;   WAIT_V(4); BAR;
.LBB0_589:
	s_or_b64 exec, exec, s[60:61]
	v_add_u32_e32 v1, v145, v1
	v_and_b32_e32 v1, 0xfffffc00, v1
	v_sub_u32_e32 v1, v145, v1
	v_lshrrev_b32_e32 v4, 4, v1
	v_bitop3_b32 v1, v4, v1, 32 bitop3:0x6c
	v_ashrrev_i32_e32 v5, 31, v1
	v_lshrrev_b32_e32 v5, 26, v5
	v_add_u32_e32 v2, v144, v2
	v_add_u32_e32 v5, v1, v5
	v_ashrrev_i32_e32 v2, 6, v2
	v_ashrrev_i32_e32 v6, 6, v5
	v_and_b32_e32 v5, 0xc0, v5
	v_lshlrev_b32_e32 v4, 3, v2
	v_lshlrev_b32_e32 v2, 5, v2
	v_sub_u32_e32 v1, v1, v5
	v_and_b32_e32 v4, -16, v4
	v_and_b32_e32 v2, 32, v2
	v_ashrrev_i16_sdwa v1, v193, sext(v1) dst_sel:DWORD dst_unused:UNUSED_PAD src0_sel:DWORD src1_sel:BYTE_0
	v_add_u32_e32 v4, v6, v4
	v_add_u32_sdwa v128, v2, sext(v1) dst_sel:DWORD dst_unused:UNUSED_PAD src0_sel:DWORD src1_sel:WORD_0
	v_ashrrev_i32_e32 v1, 31, v0
	v_ashrrev_i32_e32 v5, 31, v4
	v_lshrrev_b32_e32 v1, 22, v1
	v_lshlrev_b64 v[130:131], 13, v[4:5]
	v_ashrrev_i32_e32 v129, 31, v128
	v_readlane_b32 s5, v254, 33
	v_add_u32_e32 v1, v0, v1
	v_lshl_add_u64 v[4:5], s[58:59], 0, v[130:131]
	v_lshlrev_b64 v[6:7], 1, v[128:129]
	v_add_u32_e32 v154, s5, v145
	v_ashrrev_i32_e32 v1, 10, v1
	v_lshl_add_u64 v[4:5], v[4:5], 0, v[6:7]
	s_mov_b64 s[40:41], 0x80
	v_readfirstlane_b32 s1, v154
	v_mul_i32_i24_e32 v2, 0x400, v1
	v_lshl_add_u64 v[4:5], v[4:5], 0, s[40:41]
	s_mov_b32 m0, s1
	v_sub_u32_e32 v2, v0, v2
	s_waitcnt vmcnt(4)
	s_barrier
; #define WAIT_V(n) asm volatile("s_waitcnt vmcnt(" #n ")" ::: "memory")
; #define BAR __builtin_amdgcn_s_barrier()
; template <int K, bool SWAP>
; __device__ __forceinline__ void gemm_kloop(const bf16* __restrict__ A, const bf16* __restrict__ Bt,
;                                            f32x4 (&acc)[2][2][4][2], bool pref = false) {
;     ...
;   STAGE(SB(1, 0), Bt, 0, 1); STAGE(SA(1, 0), A, 0, 1); STAGE(SB(1, 1), Bt, HALF, 1);
;   WAIT_V(6); BAR;
; __device__ __forceinline__ void zero_acc(f32x4 (&acc)[2][2][4][2]) {
;   _Pragma("unroll") for (int a = 0; a < 2; ++a) _Pragma("unroll") for (int b = 0; b < 2; ++b) _Pragma("unroll") for (int m = 0; m < 4; ++m) _Pragma("unroll") for (int n = 0; n < 2; ++n)
;     acc[a][b][m][n] = f32x4{0.f, 0.f, 0.f, 0.f};
	global_load_lds_dwordx4 v[4:5], off
	v_lshrrev_b32_e32 v4, 4, v2
	v_bitop3_b32 v2, v4, v2, 32 bitop3:0x6c
	v_ashrrev_i32_e32 v5, 31, v2
	v_lshrrev_b32_e32 v5, 26, v5
	v_add_u32_e32 v5, v2, v5
	v_lshlrev_b32_e32 v4, 3, v1
	v_ashrrev_i32_e32 v8, 6, v5
	v_and_b32_e32 v5, 0xc0, v5
	v_and_b32_e32 v4, -16, v4
	v_lshlrev_b32_e32 v1, 5, v1
	v_sub_u32_e32 v2, v2, v5
	v_add_u32_e32 v4, v8, v4
	v_and_b32_e32 v1, 32, v1
	v_ashrrev_i16_sdwa v2, v193, sext(v2) dst_sel:DWORD dst_unused:UNUSED_PAD src0_sel:DWORD src1_sel:BYTE_0
	v_add_u32_sdwa v132, v1, sext(v2) dst_sel:DWORD dst_unused:UNUSED_PAD src0_sel:DWORD src1_sel:WORD_0
	v_ashrrev_i32_e32 v5, 31, v4
	v_lshlrev_b64 v[134:135], 13, v[4:5]
	v_ashrrev_i32_e32 v133, 31, v132
	v_lshl_add_u64 v[4:5], s[58:59], 0, v[134:135]
	v_lshlrev_b64 v[8:9], 1, v[132:133]
	v_add_u32_e32 v1, s5, v0
	v_lshl_add_u64 v[4:5], v[4:5], 0, v[8:9]
	v_readfirstlane_b32 s1, v1
	v_lshl_add_u64 v[4:5], v[4:5], 0, s[40:41]
	s_mov_b32 m0, s1
	v_add_u32_e32 v155, 0x8000, v146
	global_load_lds_dwordx4 v[4:5], off
	v_lshl_add_u64 v[4:5], s[12:13], 0, v[130:131]
	v_lshl_add_u64 v[4:5], v[4:5], 0, v[6:7]
	v_readfirstlane_b32 s1, v155
	v_lshl_add_u64 v[4:5], v[4:5], 0, s[40:41]
	s_mov_b32 m0, s1
	v_add_u32_e32 v157, 0xa000, v146
	global_load_lds_dwordx4 v[4:5], off
	v_lshl_add_u64 v[4:5], s[12:13], 0, v[134:135]
	v_lshl_add_u64 v[4:5], v[4:5], 0, v[8:9]
	v_lshl_add_u64 v[4:5], v[4:5], 0, s[40:41]
	v_readfirstlane_b32 s1, v157
	s_add_u32 s40, s58, 0x100080
	v_readlane_b32 s58, v254, 34
	s_mov_b32 m0, s1
	s_addc_u32 s41, s59, 0
	v_add_u32_e32 v158, s58, v145
	global_load_lds_dwordx4 v[4:5], off
	v_lshl_add_u64 v[4:5], s[40:41], 0, v[130:131]
	v_readfirstlane_b32 s1, v158
	v_lshl_add_u64 v[4:5], v[4:5], 0, v[6:7]
	s_mov_b32 m0, s1
	v_add_u32_e32 v0, s58, v0
	global_load_lds_dwordx4 v[4:5], off
	v_lshl_add_u64 v[4:5], s[40:41], 0, v[134:135]
	v_readfirstlane_b32 s1, v0
	v_lshl_add_u64 v[4:5], v[4:5], 0, v[8:9]
	s_mov_b32 m0, s1
	v_and_b32_e32 v10, 15, v144
	global_load_lds_dwordx4 v[4:5], off
	v_lshlrev_b32_e32 v1, 2, v144
	v_and_b32_e32 v11, 48, v144
	v_lshlrev_b32_e32 v0, 6, v10
	v_and_b32_e32 v1, 32, v1
	v_bitop3_b32 v0, v0, v1, v11 bitop3:0x36
	s_add_i32 s1, 0, 0x10000
	v_add_u32_e32 v5, s5, v0
	v_lshlrev_b32_e32 v12, 6, v144
	s_movk_i32 s5, 0x3c0
	v_add_u32_e32 v2, s1, v0
	v_add_u32_e32 v4, s33, v0
	v_add_u32_e32 v10, s58, v0
	v_add_u32_e32 v14, 0, v0
	v_and_or_b32 v0, v12, s5, v11
	v_xad_u32 v11, v0, v1, 0
	v_lshl_add_u64 v[0:1], s[22:23], 0, v[130:131]
	v_lshl_add_u64 v[136:137], v[0:1], 0, v[6:7]
	v_lshl_add_u64 v[0:1], s[22:23], 0, v[134:135]
	v_lshl_add_u64 v[138:139], v[0:1], 0, v[8:9]
	v_lshl_add_u64 v[0:1], s[14:15], 0, v[130:131]
	s_waitcnt vmcnt(6)
	v_lshlrev_b32_e32 v3, 13, v3
	v_lshl_add_u64 v[140:141], v[0:1], 0, v[6:7]
	v_lshl_add_u64 v[0:1], s[14:15], 0, v[134:135]
	v_and_b32_e32 v13, 0x3000, v12
	v_or_b32_e32 v12, 0x800, v3
	v_or_b32_e32 v15, 0x1000, v3
	v_or_b32_e32 v16, 0x1800, v3
	v_lshl_add_u64 v[142:143], v[0:1], 0, v[8:9]
	v_mov_b32_e32 v0, 0
	s_mov_b32 s5, -2
	v_add_u32_e32 v159, v2, v13
	v_add_u32_e32 v151, v14, v3
	v_add_u32_e32 v150, v11, v12
	v_add_u32_e32 v149, v11, v15
	v_add_u32_e32 v148, v11, v16
	v_add_u32_e32 v156, v4, v13
	v_add_u32_e32 v153, v5, v13
	v_add_u32_e32 v152, v10, v13
	v_mov_b32_e32 v1, v0
	v_mov_b32_e32 v2, v0
	v_mov_b32_e32 v3, v0
	v_mov_b32_e32 v4, v0
	v_mov_b32_e32 v5, v0
	v_mov_b32_e32 v6, v0
	v_mov_b32_e32 v7, v0
	v_mov_b32_e32 v8, v0
	v_mov_b32_e32 v9, v0
	v_mov_b32_e32 v10, v0
	v_mov_b32_e32 v11, v0
	v_mov_b32_e32 v12, v0
	v_mov_b32_e32 v13, v0
	v_mov_b32_e32 v14, v0
	v_mov_b32_e32 v15, v0
	v_mov_b32_e32 v16, v0
	v_mov_b32_e32 v17, v0
	v_mov_b32_e32 v18, v0
	v_mov_b32_e32 v19, v0
	v_mov_b32_e32 v20, v0
	v_mov_b32_e32 v21, v0
	v_mov_b32_e32 v22, v0
	v_mov_b32_e32 v23, v0
	v_mov_b32_e32 v24, v0
	v_mov_b32_e32 v25, v0
	v_mov_b32_e32 v26, v0
	v_mov_b32_e32 v27, v0
	v_mov_b32_e32 v28, v0
	v_mov_b32_e32 v29, v0
	v_mov_b32_e32 v30, v0
	v_mov_b32_e32 v31, v0
	v_mov_b32_e32 v32, v0
	v_mov_b32_e32 v33, v0
	v_mov_b32_e32 v34, v0
	v_mov_b32_e32 v35, v0
	v_mov_b32_e32 v36, v0
	v_mov_b32_e32 v37, v0
	v_mov_b32_e32 v38, v0
	v_mov_b32_e32 v39, v0
	v_mov_b32_e32 v40, v0
	v_mov_b32_e32 v41, v0
	v_mov_b32_e32 v42, v0
	v_mov_b32_e32 v43, v0
	v_mov_b32_e32 v44, v0
	v_mov_b32_e32 v45, v0
	v_mov_b32_e32 v46, v0
	v_mov_b32_e32 v47, v0
	v_mov_b32_e32 v48, v0
	v_mov_b32_e32 v49, v0
	v_mov_b32_e32 v50, v0
	v_mov_b32_e32 v51, v0
	v_mov_b32_e32 v52, v0
	v_mov_b32_e32 v53, v0
	v_mov_b32_e32 v54, v0
	v_mov_b32_e32 v55, v0
	v_mov_b32_e32 v56, v0
	v_mov_b32_e32 v57, v0
	v_mov_b32_e32 v58, v0
	v_mov_b32_e32 v59, v0
	v_mov_b32_e32 v60, v0
	v_mov_b32_e32 v61, v0
	v_mov_b32_e32 v62, v0
	v_mov_b32_e32 v63, v0
	v_mov_b32_e32 v64, v0
	v_mov_b32_e32 v65, v0
	v_mov_b32_e32 v66, v0
	v_mov_b32_e32 v67, v0
	v_mov_b32_e32 v68, v0
	v_mov_b32_e32 v69, v0
	v_mov_b32_e32 v70, v0
	v_mov_b32_e32 v71, v0
	v_mov_b32_e32 v72, v0
	v_mov_b32_e32 v73, v0
	v_mov_b32_e32 v74, v0
	v_mov_b32_e32 v75, v0
	v_mov_b32_e32 v76, v0
	v_mov_b32_e32 v77, v0
	v_mov_b32_e32 v78, v0
	v_mov_b32_e32 v79, v0
	v_mov_b32_e32 v80, v0
	v_mov_b32_e32 v81, v0
	v_mov_b32_e32 v82, v0
	v_mov_b32_e32 v83, v0
	v_mov_b32_e32 v84, v0
	v_mov_b32_e32 v85, v0
	v_mov_b32_e32 v86, v0
	v_mov_b32_e32 v87, v0
	v_mov_b32_e32 v88, v0
	v_mov_b32_e32 v89, v0
	v_mov_b32_e32 v90, v0
	v_mov_b32_e32 v91, v0
	v_mov_b32_e32 v92, v0
	v_mov_b32_e32 v93, v0
	v_mov_b32_e32 v94, v0
	v_mov_b32_e32 v95, v0
	v_mov_b32_e32 v96, v0
	v_mov_b32_e32 v97, v0
	v_mov_b32_e32 v98, v0
	v_mov_b32_e32 v99, v0
	v_mov_b32_e32 v100, v0
	v_mov_b32_e32 v101, v0
	v_mov_b32_e32 v102, v0
	v_mov_b32_e32 v103, v0
	v_mov_b32_e32 v104, v0
	v_mov_b32_e32 v105, v0
	v_mov_b32_e32 v106, v0
	v_mov_b32_e32 v107, v0
	v_mov_b32_e32 v108, v0
	v_mov_b32_e32 v109, v0
	v_mov_b32_e32 v110, v0
	v_mov_b32_e32 v111, v0
	v_mov_b32_e32 v112, v0
	v_mov_b32_e32 v113, v0
	v_mov_b32_e32 v114, v0
	v_mov_b32_e32 v115, v0
	v_mov_b32_e32 v116, v0
	v_mov_b32_e32 v117, v0
	v_mov_b32_e32 v118, v0
	v_mov_b32_e32 v119, v0
	v_mov_b32_e32 v120, v0
	v_mov_b32_e32 v121, v0
	v_mov_b32_e32 v122, v0
	v_mov_b32_e32 v123, v0
	v_mov_b32_e32 v124, v0
	v_mov_b32_e32 v125, v0
	v_mov_b32_e32 v126, v0
	v_mov_b32_e32 v127, v0
	s_mov_b64 s[22:23], 0x2100080
	s_mov_b64 s[40:41], 0xb260100
	s_mov_b64 s[58:59], 0x2000100
	s_mov_b64 s[60:61], 0xb360100
	s_mov_b64 s[72:73], 0x2100100
	s_mov_b64 vcc, 0xb260180
	s_mov_b64 s[64:65], 0x2000180
	s_mov_b64 s[70:71], 0xb360180
	s_barrier
	.p2align	6

; __device__ __forceinline__ void phase_attn(const Params& p, const Grp& g, int l) {
;     ...
;     char* Ks = g_shm + par * (256 * KPITCH); char* Vs = Ks + 128 * KPITCH;
;     par ^= 1;
;     _Pragma("unroll") for (int i = 0; i < 4; ++i) {
;       int row = lrow + 32 * i;
;       *(u32x4*)(Ks + row * KPITCH + lcc * 16) = kreg[i];
;       {
;         const int grp = lcc >> 2, c4 = lcc & 3, t = c4 >> 1, g0 = (c4 & 1) * 2;
;         char* vp = Vs + row * KPITCH + (grp * 32 + g0 * 8 + t * 4) * 2;
;         *(uint2*)(vp) = make_uint2(vreg[i][0], vreg[i][1]);
;         *(uint2*)(vp + 16) = make_uint2(vreg[i][2], vreg[i][3]);
;       }
;     }
;     const bool first_ = first;
;     _Pragma("unroll") for (int ks = 0; ks < 4; ++ks) qf[ks] = first_ ? qn[ks] : qf[ks];
;     if (first_) { mrun = p.sink[l * 8 + h] * LOG2E; lrun = (fq == 0) ? 1.f : 0.f; }
.Lattn_top_nowait:
	v_mov_b64_e32 v[98:99], v[62:63]
	v_mov_b64_e32 v[102:103], v[58:59]
	v_mov_b64_e32 v[106:107], v[54:55]
	v_mov_b64_e32 v[110:111], v[50:51]
	s_xor_b32 s60, s60, 1
	s_andn2_b64 vcc, exec, s[4:5]
	v_mov_b64_e32 v[96:97], v[60:61]
	v_mov_b64_e32 v[100:101], v[56:57]
	v_mov_b64_e32 v[104:105], v[52:53]
	v_mov_b64_e32 v[108:109], v[48:49]
	s_mov_b64 s[14:15], s[10:11]
	s_mov_b32 s72, s71
	s_mov_b32 s63, s64
	s_mov_b32 s66, s61
	s_mov_b32 s65, s73
	s_cbranch_vccz .LBB0_749
	.p2align	6

; #define WAIT_V(n) asm volatile("s_waitcnt vmcnt(" #n ")" ::: "memory")
; #define BAR __builtin_amdgcn_s_barrier()
; template <int K, bool SWAP>
; __device__ __forceinline__ void gemm_kloop(const bf16* __restrict__ A, const bf16* __restrict__ Bt,
;                                            f32x4 (&acc)[2][2][4][2], bool pref = false) {
;     ...
;   WAIT_V(4); BAR;
;   STAGE(SB(1, 0), Bt, 0, 1); STAGE(SA(1, 0), A, 0, 1); STAGE(SB(1, 1), Bt, HALF, 1);
.LBB0_790:
	s_or_b64 exec, exec, s[58:59]
	v_add_u32_e32 v1, v144, v1
	v_and_b32_e32 v1, 0xfffffc00, v1
	v_sub_u32_e32 v1, v144, v1
	v_lshrrev_b32_e32 v4, 4, v1
	v_bitop3_b32 v1, v4, v1, 32 bitop3:0x6c
	v_ashrrev_i32_e32 v5, 31, v1
	v_lshrrev_b32_e32 v5, 26, v5
	v_add_u32_e32 v2, v148, v2
	v_add_u32_e32 v5, v1, v5
	v_ashrrev_i32_e32 v2, 6, v2
	v_ashrrev_i32_e32 v6, 6, v5
	v_and_b32_e32 v5, 0xc0, v5
	v_lshlrev_b32_e32 v4, 3, v2
	v_lshlrev_b32_e32 v2, 5, v2
	v_sub_u32_e32 v1, v1, v5
	v_and_b32_e32 v4, -16, v4
	v_and_b32_e32 v2, 32, v2
	v_ashrrev_i16_sdwa v1, v193, sext(v1) dst_sel:DWORD dst_unused:UNUSED_PAD src0_sel:DWORD src1_sel:BYTE_0
	v_add_u32_e32 v4, v6, v4
	v_add_u32_sdwa v128, v2, sext(v1) dst_sel:DWORD dst_unused:UNUSED_PAD src0_sel:DWORD src1_sel:WORD_0
	v_ashrrev_i32_e32 v1, 31, v0
	v_ashrrev_i32_e32 v5, 31, v4
	v_lshrrev_b32_e32 v1, 22, v1
	v_lshlrev_b64 v[130:131], 10, v[4:5]
	v_ashrrev_i32_e32 v129, 31, v128
	v_readlane_b32 s20, v254, 33
	v_add_u32_e32 v1, v0, v1
	v_lshl_add_u64 v[4:5], s[22:23], 0, v[130:131]
	v_lshlrev_b64 v[6:7], 1, v[128:129]
	v_add_u32_e32 v152, s20, v144
	v_ashrrev_i32_e32 v1, 10, v1
	v_lshl_add_u64 v[4:5], v[4:5], 0, v[6:7]
	s_mov_b64 s[58:59], 0x80
	v_readfirstlane_b32 s9, v152
	v_mul_i32_i24_e32 v2, 0x400, v1
	v_lshl_add_u64 v[4:5], v[4:5], 0, s[58:59]
	s_mov_b32 m0, s9
	v_sub_u32_e32 v2, v0, v2
	s_waitcnt vmcnt(4)
	s_barrier
; #define WAIT_V(n) asm volatile("s_waitcnt vmcnt(" #n ")" ::: "memory")
; #define BAR __builtin_amdgcn_s_barrier()
; template <int K, bool SWAP>
; __device__ __forceinline__ void gemm_kloop(const bf16* __restrict__ A, const bf16* __restrict__ Bt,
;                                            f32x4 (&acc)[2][2][4][2], bool pref = false) {
;     ...
;   STAGE(SB(1, 0), Bt, 0, 1); STAGE(SA(1, 0), A, 0, 1); STAGE(SB(1, 1), Bt, HALF, 1);
;   WAIT_V(6); BAR;
; __device__ __forceinline__ void zero_acc(f32x4 (&acc)[2][2][4][2]) {
;   _Pragma("unroll") for (int a = 0; a < 2; ++a) _Pragma("unroll") for (int b = 0; b < 2; ++b) _Pragma("unroll") for (int m = 0; m < 4; ++m) _Pragma("unroll") for (int n = 0; n < 2; ++n)
;     acc[a][b][m][n] = f32x4{0.f, 0.f, 0.f, 0.f};
	global_load_lds_dwordx4 v[4:5], off
	v_lshrrev_b32_e32 v4, 4, v2
	v_bitop3_b32 v2, v4, v2, 32 bitop3:0x6c
	v_ashrrev_i32_e32 v5, 31, v2
	v_lshrrev_b32_e32 v5, 26, v5
	v_add_u32_e32 v5, v2, v5
	v_lshlrev_b32_e32 v4, 3, v1
	v_ashrrev_i32_e32 v8, 6, v5
	v_and_b32_e32 v5, 0xc0, v5
	v_and_b32_e32 v4, -16, v4
	v_lshlrev_b32_e32 v1, 5, v1
	v_sub_u32_e32 v2, v2, v5
	v_add_u32_e32 v4, v8, v4
	v_and_b32_e32 v1, 32, v1
	v_ashrrev_i16_sdwa v2, v193, sext(v2) dst_sel:DWORD dst_unused:UNUSED_PAD src0_sel:DWORD src1_sel:BYTE_0
	v_add_u32_sdwa v132, v1, sext(v2) dst_sel:DWORD dst_unused:UNUSED_PAD src0_sel:DWORD src1_sel:WORD_0
	v_ashrrev_i32_e32 v5, 31, v4
	v_lshlrev_b64 v[134:135], 10, v[4:5]
	v_ashrrev_i32_e32 v133, 31, v132
	v_lshl_add_u64 v[4:5], s[22:23], 0, v[134:135]
	v_lshlrev_b64 v[8:9], 1, v[132:133]
	v_add_u32_e32 v1, s20, v0
	v_lshl_add_u64 v[4:5], v[4:5], 0, v[8:9]
	v_readfirstlane_b32 s9, v1
	v_lshl_add_u64 v[4:5], v[4:5], 0, s[58:59]
	s_mov_b32 m0, s9
	v_add_u32_e32 v153, 0x8000, v145
	global_load_lds_dwordx4 v[4:5], off
	v_lshl_add_u64 v[4:5], s[0:1], 0, v[130:131]
	v_lshl_add_u64 v[4:5], v[4:5], 0, v[6:7]
	v_readfirstlane_b32 s9, v153
	v_lshl_add_u64 v[4:5], v[4:5], 0, s[58:59]
	s_mov_b32 m0, s9
	v_add_u32_e32 v154, 0xa000, v145
	global_load_lds_dwordx4 v[4:5], off
	v_lshl_add_u64 v[4:5], s[0:1], 0, v[134:135]
	v_lshl_add_u64 v[4:5], v[4:5], 0, v[8:9]
	v_readfirstlane_b32 s9, v154
	s_add_u32 s22, s22, 0x20080
	v_readlane_b32 s41, v254, 34
	v_lshl_add_u64 v[4:5], v[4:5], 0, s[58:59]
	s_mov_b32 m0, s9
	s_addc_u32 s23, s23, 0
	v_add_u32_e32 v155, s41, v144
	global_load_lds_dwordx4 v[4:5], off
	v_lshl_add_u64 v[4:5], s[22:23], 0, v[130:131]
	v_readfirstlane_b32 s9, v155
	v_lshl_add_u64 v[4:5], v[4:5], 0, v[6:7]
	s_mov_b32 m0, s9
	v_add_u32_e32 v0, s41, v0
	global_load_lds_dwordx4 v[4:5], off
	v_lshl_add_u64 v[4:5], s[22:23], 0, v[134:135]
	v_readfirstlane_b32 s9, v0
	v_lshl_add_u64 v[4:5], v[4:5], 0, v[8:9]
	s_mov_b32 m0, s9
	v_and_b32_e32 v10, 15, v148
	global_load_lds_dwordx4 v[4:5], off
	v_lshlrev_b32_e32 v1, 2, v148
	v_and_b32_e32 v11, 48, v148
	v_lshlrev_b32_e32 v0, 6, v10
	v_and_b32_e32 v1, 32, v1
	v_bitop3_b32 v0, v0, v1, v11 bitop3:0x36
	s_add_i32 s9, 0, 0x10000
	v_add_u32_e32 v5, s20, v0
	v_lshlrev_b32_e32 v12, 6, v148
	s_movk_i32 s20, 0x3c0
	v_add_u32_e32 v2, s9, v0
	v_add_u32_e32 v4, s33, v0
	v_add_u32_e32 v10, s41, v0
	v_add_u32_e32 v14, 0, v0
	v_and_or_b32 v0, v12, s20, v11
	v_readlane_b32 s20, v254, 58
	s_add_u32 s14, s20, s14
	s_addc_u32 s15, 0, s15
	v_xad_u32 v11, v0, v1, 0
	v_lshl_add_u64 v[0:1], s[14:15], 0, v[130:131]
	v_lshl_add_u64 v[136:137], v[0:1], 0, v[6:7]
	v_lshl_add_u64 v[0:1], s[14:15], 0, v[134:135]
	v_lshl_add_u64 v[138:139], v[0:1], 0, v[8:9]
	v_lshl_add_u64 v[0:1], s[12:13], 0, v[130:131]
	s_waitcnt vmcnt(6)
	v_lshlrev_b32_e32 v3, 13, v3
	v_lshl_add_u64 v[140:141], v[0:1], 0, v[6:7]
	v_lshl_add_u64 v[0:1], s[12:13], 0, v[134:135]
	v_and_b32_e32 v13, 0x3000, v12
	v_or_b32_e32 v12, 0x800, v3
	v_or_b32_e32 v15, 0x1000, v3
	v_or_b32_e32 v16, 0x1800, v3
	v_lshl_add_u64 v[142:143], v[0:1], 0, v[8:9]
	v_mov_b32_e32 v0, 0
	s_mov_b32 s12, -2
	v_add_u32_e32 v159, v2, v13
	v_add_u32_e32 v156, v14, v3
	v_add_u32_e32 v151, v11, v12
	v_add_u32_e32 v150, v11, v15
	v_add_u32_e32 v149, v11, v16
	v_add_u32_e32 v158, v4, v13
	v_add_u32_e32 v147, v5, v13
	v_add_u32_e32 v157, v10, v13
	v_mov_b32_e32 v1, v0
	v_mov_b32_e32 v2, v0
	v_mov_b32_e32 v3, v0
	v_mov_b32_e32 v4, v0
	v_mov_b32_e32 v5, v0
	v_mov_b32_e32 v6, v0
	v_mov_b32_e32 v7, v0
	v_mov_b32_e32 v8, v0
	v_mov_b32_e32 v9, v0
	v_mov_b32_e32 v10, v0
	v_mov_b32_e32 v11, v0
	v_mov_b32_e32 v12, v0
	v_mov_b32_e32 v13, v0
	v_mov_b32_e32 v14, v0
	v_mov_b32_e32 v15, v0
	v_mov_b32_e32 v16, v0
	v_mov_b32_e32 v17, v0
	v_mov_b32_e32 v18, v0
	v_mov_b32_e32 v19, v0
	v_mov_b32_e32 v20, v0
	v_mov_b32_e32 v21, v0
	v_mov_b32_e32 v22, v0
	v_mov_b32_e32 v23, v0
	v_mov_b32_e32 v24, v0
	v_mov_b32_e32 v25, v0
	v_mov_b32_e32 v26, v0
	v_mov_b32_e32 v27, v0
	v_mov_b32_e32 v28, v0
	v_mov_b32_e32 v29, v0
	v_mov_b32_e32 v30, v0
	v_mov_b32_e32 v31, v0
	v_mov_b32_e32 v32, v0
	v_mov_b32_e32 v33, v0
	v_mov_b32_e32 v34, v0
	v_mov_b32_e32 v35, v0
	v_mov_b32_e32 v36, v0
	v_mov_b32_e32 v37, v0
	v_mov_b32_e32 v38, v0
	v_mov_b32_e32 v39, v0
	v_mov_b32_e32 v40, v0
	v_mov_b32_e32 v41, v0
	v_mov_b32_e32 v42, v0
	v_mov_b32_e32 v43, v0
	v_mov_b32_e32 v44, v0
	v_mov_b32_e32 v45, v0
	v_mov_b32_e32 v46, v0
	v_mov_b32_e32 v47, v0
	v_mov_b32_e32 v48, v0
	v_mov_b32_e32 v49, v0
	v_mov_b32_e32 v50, v0
	v_mov_b32_e32 v51, v0
	v_mov_b32_e32 v52, v0
	v_mov_b32_e32 v53, v0
	v_mov_b32_e32 v54, v0
	v_mov_b32_e32 v55, v0
	v_mov_b32_e32 v56, v0
	v_mov_b32_e32 v57, v0
	v_mov_b32_e32 v58, v0
	v_mov_b32_e32 v59, v0
	v_mov_b32_e32 v60, v0
	v_mov_b32_e32 v61, v0
	v_mov_b32_e32 v62, v0
	v_mov_b32_e32 v63, v0
	v_mov_b32_e32 v64, v0
	v_mov_b32_e32 v65, v0
	v_mov_b32_e32 v66, v0
	v_mov_b32_e32 v67, v0
	v_mov_b32_e32 v68, v0
	v_mov_b32_e32 v69, v0
	v_mov_b32_e32 v70, v0
	v_mov_b32_e32 v71, v0
	v_mov_b32_e32 v72, v0
	v_mov_b32_e32 v73, v0
	v_mov_b32_e32 v74, v0
	v_mov_b32_e32 v75, v0
	v_mov_b32_e32 v76, v0
	v_mov_b32_e32 v77, v0
	v_mov_b32_e32 v78, v0
	v_mov_b32_e32 v79, v0
	v_mov_b32_e32 v80, v0
	v_mov_b32_e32 v81, v0
	v_mov_b32_e32 v82, v0
	v_mov_b32_e32 v83, v0
	v_mov_b32_e32 v84, v0
	v_mov_b32_e32 v85, v0
	v_mov_b32_e32 v86, v0
	v_mov_b32_e32 v87, v0
	v_mov_b32_e32 v88, v0
	v_mov_b32_e32 v89, v0
	v_mov_b32_e32 v90, v0
	v_mov_b32_e32 v91, v0
	v_mov_b32_e32 v92, v0
	v_mov_b32_e32 v93, v0
	v_mov_b32_e32 v94, v0
	v_mov_b32_e32 v95, v0
	v_mov_b32_e32 v96, v0
	v_mov_b32_e32 v97, v0
	v_mov_b32_e32 v98, v0
	v_mov_b32_e32 v99, v0
	v_mov_b32_e32 v100, v0
	v_mov_b32_e32 v101, v0
	v_mov_b32_e32 v102, v0
	v_mov_b32_e32 v103, v0
	v_mov_b32_e32 v104, v0
	v_mov_b32_e32 v105, v0
	v_mov_b32_e32 v106, v0
	v_mov_b32_e32 v107, v0
	v_mov_b32_e32 v108, v0
	v_mov_b32_e32 v109, v0
	v_mov_b32_e32 v110, v0
	v_mov_b32_e32 v111, v0
	v_mov_b32_e32 v112, v0
	v_mov_b32_e32 v113, v0
	v_mov_b32_e32 v114, v0
	v_mov_b32_e32 v115, v0
	v_mov_b32_e32 v116, v0
	v_mov_b32_e32 v117, v0
	v_mov_b32_e32 v118, v0
	v_mov_b32_e32 v119, v0
	v_mov_b32_e32 v120, v0
	v_mov_b32_e32 v121, v0
	v_mov_b32_e32 v122, v0
	v_mov_b32_e32 v123, v0
	v_mov_b32_e32 v124, v0
	v_mov_b32_e32 v125, v0
	v_mov_b32_e32 v126, v0
	v_mov_b32_e32 v127, v0
	s_barrier
	.p2align	6

; #define WAIT_V(n) asm volatile("s_waitcnt vmcnt(" #n ")" ::: "memory")
; #define BAR __builtin_amdgcn_s_barrier()
; template <int K, bool SWAP>
; __device__ __forceinline__ void gemm_kloop(const bf16* __restrict__ A, const bf16* __restrict__ Bt,
;                                            f32x4 (&acc)[2][2][4][2], bool pref = false) {
;     ...
;   WAIT_V(4); BAR;
;   STAGE(SB(1, 0), Bt, 0, 1); STAGE(SA(1, 0), A, 0, 1); STAGE(SB(1, 1), Bt, HALF, 1);
.LBB0_796:
	s_or_b64 exec, exec, s[62:63]
	v_ashrrev_i32_e32 v2, 31, v144
	v_lshrrev_b32_e32 v2, 26, v2
	v_add_u32_e32 v2, v144, v2
	v_ashrrev_i32_e32 v3, 6, v2
	v_bfe_i32 v2, v144, 27, 1
	v_lshlrev_b32_e32 v150, 4, v144
	v_lshrrev_b32_e32 v2, 22, v2
	v_add_u32_e32 v2, v150, v2
	v_and_b32_e32 v2, 0xfffffc00, v2
	v_sub_u32_e32 v2, v150, v2
	v_lshrrev_b32_e32 v4, 4, v2
	v_bitop3_b32 v4, v4, v2, 32 bitop3:0x6c
	v_ashrrev_i32_e32 v5, 31, v4
	v_lshrrev_b32_e32 v5, 26, v5
	v_add_u32_e32 v5, v4, v5
	v_lshlrev_b32_e32 v2, 3, v3
	v_ashrrev_i32_e32 v6, 6, v5
	v_and_b32_e32 v5, 0xc0, v5
	v_and_b32_e32 v2, -16, v2
	v_lshlrev_b32_e32 v3, 5, v3
	v_sub_u32_e32 v4, v4, v5
	v_add_u32_e32 v2, v6, v2
	v_and_b32_e32 v3, 32, v3
	v_ashrrev_i16_sdwa v4, v193, sext(v4) dst_sel:DWORD dst_unused:UNUSED_PAD src0_sel:DWORD src1_sel:BYTE_0
	v_add_u32_sdwa v128, v3, sext(v4) dst_sel:DWORD dst_unused:UNUSED_PAD src0_sel:DWORD src1_sel:WORD_0
	v_ashrrev_i32_e32 v3, 31, v2
	v_lshlrev_b64 v[130:131], 11, v[2:3]
	v_ashrrev_i32_e32 v129, 31, v128
	v_readlane_b32 s5, v254, 33
	v_lshl_add_u64 v[2:3], s[60:61], 0, v[130:131]
	v_lshlrev_b64 v[4:5], 1, v[128:129]
	v_add_u32_e32 v152, s5, v150
	v_lshl_add_u64 v[2:3], v[2:3], 0, v[4:5]
	s_mov_b64 s[40:41], 0x80
	v_readfirstlane_b32 s1, v152
	v_lshl_add_u64 v[2:3], v[2:3], 0, s[40:41]
	s_mov_b32 m0, s1
	v_add_u32_e32 v9, 0x2000, v150
	s_waitcnt vmcnt(4)
	s_barrier
; #define WAIT_V(n) asm volatile("s_waitcnt vmcnt(" #n ")" ::: "memory")
; #define BAR __builtin_amdgcn_s_barrier()
; template <int K, bool SWAP>
; __device__ __forceinline__ void gemm_kloop(const bf16* __restrict__ A, const bf16* __restrict__ Bt,
;                                            f32x4 (&acc)[2][2][4][2], bool pref = false) {
;     ...
;   STAGE(SB(1, 0), Bt, 0, 1); STAGE(SA(1, 0), A, 0, 1); STAGE(SB(1, 1), Bt, HALF, 1);
;   WAIT_V(6); BAR;
; __device__ __forceinline__ void zero_acc(f32x4 (&acc)[2][2][4][2]) {
;   _Pragma("unroll") for (int a = 0; a < 2; ++a) _Pragma("unroll") for (int b = 0; b < 2; ++b) _Pragma("unroll") for (int m = 0; m < 4; ++m) _Pragma("unroll") for (int n = 0; n < 2; ++n)
;     acc[a][b][m][n] = f32x4{0.f, 0.f, 0.f, 0.f};
	global_load_lds_dwordx4 v[2:3], off
	v_ashrrev_i32_e32 v2, 31, v9
	v_lshrrev_b32_e32 v2, 22, v2
	v_add_u32_e32 v2, v9, v2
	v_ashrrev_i32_e32 v3, 10, v2
	v_mul_i32_i24_e32 v2, 0x400, v3
	v_sub_u32_e32 v2, v9, v2
	v_lshrrev_b32_e32 v6, 4, v2
	v_bitop3_b32 v6, v6, v2, 32 bitop3:0x6c
	v_ashrrev_i32_e32 v7, 31, v6
	v_lshrrev_b32_e32 v7, 26, v7
	v_add_u32_e32 v7, v6, v7
	v_lshlrev_b32_e32 v2, 3, v3
	v_ashrrev_i32_e32 v10, 6, v7
	v_and_b32_e32 v7, 0xc0, v7
	v_and_b32_e32 v2, -16, v2
	v_lshlrev_b32_e32 v3, 5, v3
	v_sub_u32_e32 v6, v6, v7
	v_add_u32_e32 v2, v10, v2
	v_and_b32_e32 v3, 32, v3
	v_ashrrev_i16_sdwa v6, v193, sext(v6) dst_sel:DWORD dst_unused:UNUSED_PAD src0_sel:DWORD src1_sel:BYTE_0
	v_add_u32_sdwa v132, v3, sext(v6) dst_sel:DWORD dst_unused:UNUSED_PAD src0_sel:DWORD src1_sel:WORD_0
	v_ashrrev_i32_e32 v3, 31, v2
	v_lshlrev_b64 v[134:135], 11, v[2:3]
	v_ashrrev_i32_e32 v133, 31, v132
	v_lshl_add_u64 v[2:3], s[60:61], 0, v[134:135]
	v_lshlrev_b64 v[6:7], 1, v[132:133]
	v_add_u32_e32 v10, s5, v9
	v_lshl_add_u64 v[2:3], v[2:3], 0, v[6:7]
	v_readfirstlane_b32 s1, v10
	v_lshl_add_u64 v[2:3], v[2:3], 0, s[40:41]
	s_mov_b32 m0, s1
	v_add_u32_e32 v153, 0, v150
	global_load_lds_dwordx4 v[2:3], off
	v_lshl_add_u64 v[2:3], s[14:15], 0, v[130:131]
	v_add_u32_e32 v154, 0x8000, v153
	v_lshl_add_u64 v[2:3], v[2:3], 0, v[4:5]
	v_readfirstlane_b32 s1, v154
	v_lshl_add_u64 v[2:3], v[2:3], 0, s[40:41]
	s_mov_b32 m0, s1
	v_add_u32_e32 v155, 0xa000, v153
	global_load_lds_dwordx4 v[2:3], off
	v_lshl_add_u64 v[2:3], s[14:15], 0, v[134:135]
	v_lshl_add_u64 v[2:3], v[2:3], 0, v[6:7]
	v_lshl_add_u64 v[2:3], v[2:3], 0, s[40:41]
	v_readfirstlane_b32 s1, v155
	s_add_u32 s40, s60, 0x40080
	v_readlane_b32 s11, v254, 34
	s_mov_b32 m0, s1
	s_addc_u32 s41, s61, 0
	v_add_u32_e32 v156, s11, v150
	global_load_lds_dwordx4 v[2:3], off
	v_lshl_add_u64 v[2:3], s[40:41], 0, v[130:131]
	v_readfirstlane_b32 s1, v156
	v_lshl_add_u64 v[2:3], v[2:3], 0, v[4:5]
	s_mov_b32 m0, s1
	v_add_u32_e32 v9, s11, v9
	global_load_lds_dwordx4 v[2:3], off
	v_lshl_add_u64 v[2:3], s[40:41], 0, v[134:135]
	v_readfirstlane_b32 s1, v9
	v_lshl_add_u64 v[2:3], v[2:3], 0, v[6:7]
	s_mov_b32 m0, s1
	v_and_b32_e32 v8, 48, v144
	global_load_lds_dwordx4 v[2:3], off
	v_lshlrev_b32_e32 v12, 6, v144
	s_movk_i32 s1, 0x3c0
	v_and_b32_e32 v1, 15, v144
	v_lshlrev_b32_e32 v2, 2, v144
	v_lshlrev_b32_e32 v14, 13, v0
	v_and_or_b32 v0, v12, s1, v8
	v_readlane_b32 s1, v254, 59
	v_lshlrev_b32_e32 v1, 6, v1
	v_and_b32_e32 v2, 32, v2
	s_add_u32 s40, s1, s58
	v_bitop3_b32 v1, v1, v2, v8 bitop3:0x36
	s_addc_u32 s41, 0, s59
	v_add_u32_e32 v3, s9, v1
	v_add_u32_e32 v9, s33, v1
	v_add_u32_e32 v10, s5, v1
	v_add_u32_e32 v11, s11, v1
	v_add_u32_e32 v15, 0, v1
	v_xad_u32 v2, v0, v2, 0
	v_lshl_add_u64 v[0:1], s[40:41], 0, v[130:131]
	v_lshl_add_u64 v[136:137], v[0:1], 0, v[4:5]
	v_lshl_add_u64 v[0:1], s[40:41], 0, v[134:135]
	v_lshl_add_u64 v[138:139], v[0:1], 0, v[6:7]
	v_lshl_add_u64 v[0:1], s[22:23], 0, v[130:131]
	s_waitcnt vmcnt(6)
	v_lshl_add_u64 v[140:141], v[0:1], 0, v[4:5]
	v_lshl_add_u64 v[0:1], s[22:23], 0, v[134:135]
	v_and_b32_e32 v13, 0x3000, v12
	v_or_b32_e32 v8, 0x800, v14
	v_or_b32_e32 v12, 0x1000, v14
	v_or_b32_e32 v16, 0x1800, v14
	v_lshl_add_u64 v[142:143], v[0:1], 0, v[6:7]
	v_mov_b32_e32 v0, 0
	s_mov_b32 s1, -2
	v_add_u32_e32 v158, v3, v13
	v_add_u32_e32 v148, v15, v14
	v_add_u32_e32 v147, v2, v8
	v_add_u32_e32 v146, v2, v12
	v_add_u32_e32 v145, v2, v16
	v_add_u32_e32 v157, v9, v13
	v_add_u32_e32 v151, v10, v13
	v_add_u32_e32 v149, v11, v13
	v_mov_b32_e32 v1, v0
	v_mov_b32_e32 v2, v0
	v_mov_b32_e32 v3, v0
	v_mov_b32_e32 v4, v0
	v_mov_b32_e32 v5, v0
	v_mov_b32_e32 v6, v0
	v_mov_b32_e32 v7, v0
	v_mov_b32_e32 v8, v0
	v_mov_b32_e32 v9, v0
	v_mov_b32_e32 v10, v0
	v_mov_b32_e32 v11, v0
	v_mov_b32_e32 v12, v0
	v_mov_b32_e32 v13, v0
	v_mov_b32_e32 v14, v0
	v_mov_b32_e32 v15, v0
	v_mov_b32_e32 v16, v0
	v_mov_b32_e32 v17, v0
	v_mov_b32_e32 v18, v0
	v_mov_b32_e32 v19, v0
	v_mov_b32_e32 v20, v0
	v_mov_b32_e32 v21, v0
	v_mov_b32_e32 v22, v0
	v_mov_b32_e32 v23, v0
	v_mov_b32_e32 v24, v0
	v_mov_b32_e32 v25, v0
	v_mov_b32_e32 v26, v0
	v_mov_b32_e32 v27, v0
	v_mov_b32_e32 v28, v0
	v_mov_b32_e32 v29, v0
	v_mov_b32_e32 v30, v0
	v_mov_b32_e32 v31, v0
	v_mov_b32_e32 v32, v0
	v_mov_b32_e32 v33, v0
	v_mov_b32_e32 v34, v0
	v_mov_b32_e32 v35, v0
	v_mov_b32_e32 v36, v0
	v_mov_b32_e32 v37, v0
	v_mov_b32_e32 v38, v0
	v_mov_b32_e32 v39, v0
	v_mov_b32_e32 v40, v0
	v_mov_b32_e32 v41, v0
	v_mov_b32_e32 v42, v0
	v_mov_b32_e32 v43, v0
	v_mov_b32_e32 v44, v0
	v_mov_b32_e32 v45, v0
	v_mov_b32_e32 v46, v0
	v_mov_b32_e32 v47, v0
	v_mov_b32_e32 v48, v0
	v_mov_b32_e32 v49, v0
	v_mov_b32_e32 v50, v0
	v_mov_b32_e32 v51, v0
	v_mov_b32_e32 v52, v0
	v_mov_b32_e32 v53, v0
	v_mov_b32_e32 v54, v0
	v_mov_b32_e32 v55, v0
	v_mov_b32_e32 v56, v0
	v_mov_b32_e32 v57, v0
	v_mov_b32_e32 v58, v0
	v_mov_b32_e32 v59, v0
	v_mov_b32_e32 v60, v0
	v_mov_b32_e32 v61, v0
	v_mov_b32_e32 v62, v0
	v_mov_b32_e32 v63, v0
	v_mov_b32_e32 v64, v0
	v_mov_b32_e32 v65, v0
	v_mov_b32_e32 v66, v0
	v_mov_b32_e32 v67, v0
	v_mov_b32_e32 v68, v0
	v_mov_b32_e32 v69, v0
	v_mov_b32_e32 v70, v0
	v_mov_b32_e32 v71, v0
	v_mov_b32_e32 v72, v0
	v_mov_b32_e32 v73, v0
	v_mov_b32_e32 v74, v0
	v_mov_b32_e32 v75, v0
	v_mov_b32_e32 v76, v0
	v_mov_b32_e32 v77, v0
	v_mov_b32_e32 v78, v0
	v_mov_b32_e32 v79, v0
	v_mov_b32_e32 v80, v0
	v_mov_b32_e32 v81, v0
	v_mov_b32_e32 v82, v0
	v_mov_b32_e32 v83, v0
	v_mov_b32_e32 v84, v0
	v_mov_b32_e32 v85, v0
	v_mov_b32_e32 v86, v0
	v_mov_b32_e32 v87, v0
	v_mov_b32_e32 v88, v0
	v_mov_b32_e32 v89, v0
	v_mov_b32_e32 v90, v0
	v_mov_b32_e32 v91, v0
	v_mov_b32_e32 v92, v0
	v_mov_b32_e32 v93, v0
	v_mov_b32_e32 v94, v0
	v_mov_b32_e32 v95, v0
	v_mov_b32_e32 v96, v0
	v_mov_b32_e32 v97, v0
	v_mov_b32_e32 v98, v0
	v_mov_b32_e32 v99, v0
	v_mov_b32_e32 v100, v0
	v_mov_b32_e32 v101, v0
	v_mov_b32_e32 v102, v0
	v_mov_b32_e32 v103, v0
	v_mov_b32_e32 v104, v0
	v_mov_b32_e32 v105, v0
	v_mov_b32_e32 v106, v0
	v_mov_b32_e32 v107, v0
	v_mov_b32_e32 v108, v0
	v_mov_b32_e32 v109, v0
	v_mov_b32_e32 v110, v0
	v_mov_b32_e32 v111, v0
	v_mov_b32_e32 v112, v0
	v_mov_b32_e32 v113, v0
	v_mov_b32_e32 v114, v0
	v_mov_b32_e32 v115, v0
	v_mov_b32_e32 v116, v0
	v_mov_b32_e32 v117, v0
	v_mov_b32_e32 v118, v0
	v_mov_b32_e32 v119, v0
	v_mov_b32_e32 v120, v0
	v_mov_b32_e32 v121, v0
	v_mov_b32_e32 v122, v0
	v_mov_b32_e32 v123, v0
	v_mov_b32_e32 v124, v0
	v_mov_b32_e32 v125, v0
	v_mov_b32_e32 v126, v0
	v_mov_b32_e32 v127, v0
	s_barrier
	.p2align	6

; #define WAIT_V(n) asm volatile("s_waitcnt vmcnt(" #n ")" ::: "memory")
; #define BAR __builtin_amdgcn_s_barrier()
; template <int K, bool SWAP>
; __device__ __forceinline__ void gemm_kloop(const bf16* __restrict__ A, const bf16* __restrict__ Bt,
;                                            f32x4 (&acc)[2][2][4][2], bool pref = false) {
;     ...
;   WAIT_V(4); BAR;
;   STAGE(SB(1, 0), Bt, 0, 1); STAGE(SA(1, 0), A, 0, 1); STAGE(SB(1, 1), Bt, HALF, 1);
.LBB0_843:
	s_or_b64 exec, exec, s[60:61]
	v_add_u32_e32 v1, v145, v1
	v_and_b32_e32 v1, 0xfffffc00, v1
	v_sub_u32_e32 v1, v145, v1
	v_lshrrev_b32_e32 v4, 4, v1
	v_bitop3_b32 v1, v4, v1, 32 bitop3:0x6c
	v_ashrrev_i32_e32 v5, 31, v1
	v_lshrrev_b32_e32 v5, 26, v5
	v_add_u32_e32 v2, v144, v2
	v_add_u32_e32 v5, v1, v5
	v_ashrrev_i32_e32 v2, 6, v2
	v_ashrrev_i32_e32 v6, 6, v5
	v_and_b32_e32 v5, 0xc0, v5
	v_lshlrev_b32_e32 v4, 3, v2
	v_lshlrev_b32_e32 v2, 5, v2
	v_sub_u32_e32 v1, v1, v5
	v_and_b32_e32 v4, -16, v4
	v_and_b32_e32 v2, 32, v2
	v_ashrrev_i16_sdwa v1, v193, sext(v1) dst_sel:DWORD dst_unused:UNUSED_PAD src0_sel:DWORD src1_sel:BYTE_0
	v_add_u32_e32 v4, v6, v4
	v_add_u32_sdwa v128, v2, sext(v1) dst_sel:DWORD dst_unused:UNUSED_PAD src0_sel:DWORD src1_sel:WORD_0
	v_ashrrev_i32_e32 v1, 31, v0
	v_ashrrev_i32_e32 v5, 31, v4
	v_lshrrev_b32_e32 v1, 22, v1
	v_lshlrev_b64 v[130:131], 11, v[4:5]
	v_ashrrev_i32_e32 v129, 31, v128
	v_readlane_b32 s11, v254, 33
	v_add_u32_e32 v1, v0, v1
	v_lshl_add_u64 v[4:5], s[58:59], 0, v[130:131]
	v_lshlrev_b64 v[6:7], 1, v[128:129]
	v_add_u32_e32 v154, s11, v145
	v_ashrrev_i32_e32 v1, 10, v1
	v_lshl_add_u64 v[4:5], v[4:5], 0, v[6:7]
	s_mov_b64 s[60:61], 0x80
	v_readfirstlane_b32 s9, v154
	v_mul_i32_i24_e32 v2, 0x400, v1
	v_lshl_add_u64 v[4:5], v[4:5], 0, s[60:61]
	s_mov_b32 m0, s9
	v_sub_u32_e32 v2, v0, v2
	s_waitcnt vmcnt(4)
	s_barrier
; #define WAIT_V(n) asm volatile("s_waitcnt vmcnt(" #n ")" ::: "memory")
; #define BAR __builtin_amdgcn_s_barrier()
; template <int K, bool SWAP>
; __device__ __forceinline__ void gemm_kloop(const bf16* __restrict__ A, const bf16* __restrict__ Bt,
;                                            f32x4 (&acc)[2][2][4][2], bool pref = false) {
;     ...
;   STAGE(SB(1, 0), Bt, 0, 1); STAGE(SA(1, 0), A, 0, 1); STAGE(SB(1, 1), Bt, HALF, 1);
;   WAIT_V(6); BAR;
; __device__ __forceinline__ void zero_acc(f32x4 (&acc)[2][2][4][2]) {
;   _Pragma("unroll") for (int a = 0; a < 2; ++a) _Pragma("unroll") for (int b = 0; b < 2; ++b) _Pragma("unroll") for (int m = 0; m < 4; ++m) _Pragma("unroll") for (int n = 0; n < 2; ++n)
;     acc[a][b][m][n] = f32x4{0.f, 0.f, 0.f, 0.f};
	global_load_lds_dwordx4 v[4:5], off
	v_lshrrev_b32_e32 v4, 4, v2
	v_bitop3_b32 v2, v4, v2, 32 bitop3:0x6c
	v_ashrrev_i32_e32 v5, 31, v2
	v_lshrrev_b32_e32 v5, 26, v5
	v_add_u32_e32 v5, v2, v5
	v_lshlrev_b32_e32 v4, 3, v1
	v_ashrrev_i32_e32 v8, 6, v5
	v_and_b32_e32 v5, 0xc0, v5
	v_and_b32_e32 v4, -16, v4
	v_lshlrev_b32_e32 v1, 5, v1
	v_sub_u32_e32 v2, v2, v5
	v_add_u32_e32 v4, v8, v4
	v_and_b32_e32 v1, 32, v1
	v_ashrrev_i16_sdwa v2, v193, sext(v2) dst_sel:DWORD dst_unused:UNUSED_PAD src0_sel:DWORD src1_sel:BYTE_0
	v_add_u32_sdwa v132, v1, sext(v2) dst_sel:DWORD dst_unused:UNUSED_PAD src0_sel:DWORD src1_sel:WORD_0
	v_ashrrev_i32_e32 v5, 31, v4
	v_lshlrev_b64 v[134:135], 11, v[4:5]
	v_ashrrev_i32_e32 v133, 31, v132
	v_lshl_add_u64 v[4:5], s[58:59], 0, v[134:135]
	v_lshlrev_b64 v[8:9], 1, v[132:133]
	v_add_u32_e32 v1, s11, v0
	v_lshl_add_u64 v[4:5], v[4:5], 0, v[8:9]
	v_readfirstlane_b32 s9, v1
	v_lshl_add_u64 v[4:5], v[4:5], 0, s[60:61]
	s_mov_b32 m0, s9
	v_add_u32_e32 v155, 0x8000, v146
	global_load_lds_dwordx4 v[4:5], off
	v_lshl_add_u64 v[4:5], s[12:13], 0, v[130:131]
	v_lshl_add_u64 v[4:5], v[4:5], 0, v[6:7]
	v_readfirstlane_b32 s9, v155
	v_lshl_add_u64 v[4:5], v[4:5], 0, s[60:61]
	s_mov_b32 m0, s9
	v_add_u32_e32 v156, 0xa000, v146
	global_load_lds_dwordx4 v[4:5], off
	v_lshl_add_u64 v[4:5], s[12:13], 0, v[134:135]
	v_lshl_add_u64 v[4:5], v[4:5], 0, v[8:9]
	v_lshl_add_u64 v[4:5], v[4:5], 0, s[60:61]
	v_readfirstlane_b32 s9, v156
	s_add_u32 s58, s58, 0x40080
	v_readlane_b32 s60, v254, 34
	s_mov_b32 m0, s9
	s_addc_u32 s59, s59, 0
	v_add_u32_e32 v157, s60, v145
	global_load_lds_dwordx4 v[4:5], off
	v_lshl_add_u64 v[4:5], s[58:59], 0, v[130:131]
	v_readfirstlane_b32 s9, v157
	v_lshl_add_u64 v[4:5], v[4:5], 0, v[6:7]
	s_mov_b32 m0, s9
	v_add_u32_e32 v0, s60, v0
	global_load_lds_dwordx4 v[4:5], off
	v_lshl_add_u64 v[4:5], s[58:59], 0, v[134:135]
	v_readfirstlane_b32 s9, v0
	v_lshl_add_u64 v[4:5], v[4:5], 0, v[8:9]
	s_mov_b32 m0, s9
	v_and_b32_e32 v10, 15, v144
	global_load_lds_dwordx4 v[4:5], off
	v_lshlrev_b32_e32 v1, 2, v144
	v_and_b32_e32 v11, 48, v144
	v_lshlrev_b32_e32 v0, 6, v10
	v_and_b32_e32 v1, 32, v1
	v_bitop3_b32 v0, v0, v1, v11 bitop3:0x36
	s_add_i32 s9, 0, 0x10000
	v_add_u32_e32 v5, s11, v0
	v_lshlrev_b32_e32 v12, 6, v144
	s_movk_i32 s11, 0x3c0
	s_add_u32 s22, s62, s22
	v_add_u32_e32 v2, s9, v0
	v_add_u32_e32 v4, s33, v0
	v_add_u32_e32 v10, s60, v0
	v_add_u32_e32 v14, 0, v0
	v_and_or_b32 v0, v12, s11, v11
	s_addc_u32 s23, 0, s23
	v_xad_u32 v11, v0, v1, 0
	v_lshl_add_u64 v[0:1], s[22:23], 0, v[130:131]
	v_lshl_add_u64 v[136:137], v[0:1], 0, v[6:7]
	v_lshl_add_u64 v[0:1], s[22:23], 0, v[134:135]
	v_lshl_add_u64 v[138:139], v[0:1], 0, v[8:9]
	v_lshl_add_u64 v[0:1], s[14:15], 0, v[130:131]
	s_waitcnt vmcnt(6)
	v_lshlrev_b32_e32 v3, 13, v3
	v_lshl_add_u64 v[140:141], v[0:1], 0, v[6:7]
	v_lshl_add_u64 v[0:1], s[14:15], 0, v[134:135]
	v_and_b32_e32 v13, 0x3000, v12
	v_or_b32_e32 v12, 0x800, v3
	v_or_b32_e32 v15, 0x1000, v3
	v_or_b32_e32 v16, 0x1800, v3
	v_lshl_add_u64 v[142:143], v[0:1], 0, v[8:9]
	v_mov_b32_e32 v0, 0
	s_mov_b32 s11, -2
	v_add_u32_e32 v159, v2, v13
	v_add_u32_e32 v151, v14, v3
	v_add_u32_e32 v150, v11, v12
	v_add_u32_e32 v149, v11, v15
	v_add_u32_e32 v148, v11, v16
	v_add_u32_e32 v158, v4, v13
	v_add_u32_e32 v153, v5, v13
	v_add_u32_e32 v152, v10, v13
	v_mov_b32_e32 v1, v0
	v_mov_b32_e32 v2, v0
	v_mov_b32_e32 v3, v0
	v_mov_b32_e32 v4, v0
	v_mov_b32_e32 v5, v0
	v_mov_b32_e32 v6, v0
	v_mov_b32_e32 v7, v0
	v_mov_b32_e32 v8, v0
	v_mov_b32_e32 v9, v0
	v_mov_b32_e32 v10, v0
	v_mov_b32_e32 v11, v0
	v_mov_b32_e32 v12, v0
	v_mov_b32_e32 v13, v0
	v_mov_b32_e32 v14, v0
	v_mov_b32_e32 v15, v0
	v_mov_b32_e32 v16, v0
	v_mov_b32_e32 v17, v0
	v_mov_b32_e32 v18, v0
	v_mov_b32_e32 v19, v0
	v_mov_b32_e32 v20, v0
	v_mov_b32_e32 v21, v0
	v_mov_b32_e32 v22, v0
	v_mov_b32_e32 v23, v0
	v_mov_b32_e32 v24, v0
	v_mov_b32_e32 v25, v0
	v_mov_b32_e32 v26, v0
	v_mov_b32_e32 v27, v0
	v_mov_b32_e32 v28, v0
	v_mov_b32_e32 v29, v0
	v_mov_b32_e32 v30, v0
	v_mov_b32_e32 v31, v0
	v_mov_b32_e32 v32, v0
	v_mov_b32_e32 v33, v0
	v_mov_b32_e32 v34, v0
	v_mov_b32_e32 v35, v0
	v_mov_b32_e32 v36, v0
	v_mov_b32_e32 v37, v0
	v_mov_b32_e32 v38, v0
	v_mov_b32_e32 v39, v0
	v_mov_b32_e32 v40, v0
	v_mov_b32_e32 v41, v0
	v_mov_b32_e32 v42, v0
	v_mov_b32_e32 v43, v0
	v_mov_b32_e32 v44, v0
	v_mov_b32_e32 v45, v0
	v_mov_b32_e32 v46, v0
	v_mov_b32_e32 v47, v0
	v_mov_b32_e32 v48, v0
	v_mov_b32_e32 v49, v0
	v_mov_b32_e32 v50, v0
	v_mov_b32_e32 v51, v0
	v_mov_b32_e32 v52, v0
	v_mov_b32_e32 v53, v0
	v_mov_b32_e32 v54, v0
	v_mov_b32_e32 v55, v0
	v_mov_b32_e32 v56, v0
	v_mov_b32_e32 v57, v0
	v_mov_b32_e32 v58, v0
	v_mov_b32_e32 v59, v0
	v_mov_b32_e32 v60, v0
	v_mov_b32_e32 v61, v0
	v_mov_b32_e32 v62, v0
	v_mov_b32_e32 v63, v0
	v_mov_b32_e32 v64, v0
	v_mov_b32_e32 v65, v0
	v_mov_b32_e32 v66, v0
	v_mov_b32_e32 v67, v0
	v_mov_b32_e32 v68, v0
	v_mov_b32_e32 v69, v0
	v_mov_b32_e32 v70, v0
	v_mov_b32_e32 v71, v0
	v_mov_b32_e32 v72, v0
	v_mov_b32_e32 v73, v0
	v_mov_b32_e32 v74, v0
	v_mov_b32_e32 v75, v0
	v_mov_b32_e32 v76, v0
	v_mov_b32_e32 v77, v0
	v_mov_b32_e32 v78, v0
	v_mov_b32_e32 v79, v0
	v_mov_b32_e32 v80, v0
	v_mov_b32_e32 v81, v0
	v_mov_b32_e32 v82, v0
	v_mov_b32_e32 v83, v0
	v_mov_b32_e32 v84, v0
	v_mov_b32_e32 v85, v0
	v_mov_b32_e32 v86, v0
	v_mov_b32_e32 v87, v0
	v_mov_b32_e32 v88, v0
	v_mov_b32_e32 v89, v0
	v_mov_b32_e32 v90, v0
	v_mov_b32_e32 v91, v0
	v_mov_b32_e32 v92, v0
	v_mov_b32_e32 v93, v0
	v_mov_b32_e32 v94, v0
	v_mov_b32_e32 v95, v0
	v_mov_b32_e32 v96, v0
	v_mov_b32_e32 v97, v0
	v_mov_b32_e32 v98, v0
	v_mov_b32_e32 v99, v0
	v_mov_b32_e32 v100, v0
	v_mov_b32_e32 v101, v0
	v_mov_b32_e32 v102, v0
	v_mov_b32_e32 v103, v0
	v_mov_b32_e32 v104, v0
	v_mov_b32_e32 v105, v0
	v_mov_b32_e32 v106, v0
	v_mov_b32_e32 v107, v0
	v_mov_b32_e32 v108, v0
	v_mov_b32_e32 v109, v0
	v_mov_b32_e32 v110, v0
	v_mov_b32_e32 v111, v0
	v_mov_b32_e32 v112, v0
	v_mov_b32_e32 v113, v0
	v_mov_b32_e32 v114, v0
	v_mov_b32_e32 v115, v0
	v_mov_b32_e32 v116, v0
	v_mov_b32_e32 v117, v0
	v_mov_b32_e32 v118, v0
	v_mov_b32_e32 v119, v0
	v_mov_b32_e32 v120, v0
	v_mov_b32_e32 v121, v0
	v_mov_b32_e32 v122, v0
	v_mov_b32_e32 v123, v0
	v_mov_b32_e32 v124, v0
	v_mov_b32_e32 v125, v0
	v_mov_b32_e32 v126, v0
	v_mov_b32_e32 v127, v0
	s_barrier
	.p2align	6
